# load segment waits only for the ds_reads the pre-barrier MFMAs consume (counted lgkmcnt), the rest after the barrier
# baseline (speedup 1.0000x reference)
; #define PG8_STAGE(bufoff, gbase, voff) do { _Pragma("unroll") for (int _i = 0; _i < 2; ++_i) \
;         __builtin_amdgcn_global_load_lds((const unsigned*)((const char*)(gbase) + (voff)[_i]), (PG8_LAS unsigned*)(lds + (bufoff) + ldsw + _i * 8192), 16, 0, 0); } while (0)
; #define PG8_LDA(dst, b, h) do { _Pragma("unroll") for (int m = 0; m < 4; ++m) _Pragma("unroll") for (int k = 0; k < 2; ++k) dst[m][k] = *(const PG8_LAS bf16x8*)(lds + PG8_SA(b, h) + aoff + m * 2048 + k * 1024); } while (0)
; #define PG8_LDB(dst, b, h) do { _Pragma("unroll") for (int n = 0; n < 2; ++n) _Pragma("unroll") for (int k = 0; k < 2; ++k) dst[n][k] = *(const PG8_LAS bf16x8*)(lds + PG8_SB(b, h) + boff + n * 2048 + k * 1024); } while (0)
; #define PG8_MMA(ai, bj, At, Bt) do { __builtin_amdgcn_s_setprio(1); _Pragma("unroll") for (int m = 0; m < 4; ++m) _Pragma("unroll") for (int n = 0; n < 2; ++n) _Pragma("unroll") for (int k = 0; k < 2; ++k) \
;         acc[ai][bj][m][n] = __builtin_amdgcn_mfma_f32_16x16x32_bf16(Bt[n][k], At[m][k], acc[ai][bj][m][n], 0, 0, 0); __builtin_amdgcn_s_setprio(0); } while (0)
; #define PG8_WAIT_V(n) asm volatile("s_waitcnt vmcnt(" #n ")" ::: "memory")
; #define PG8_BAR __builtin_amdgcn_s_barrier()
; template <class Epi, class Sched, bool ALIGN_EPI = false, bool SP2 = false, bool ABLK = false, bool BBLK = false>
; __device__ __forceinline__ void gemm_phase(PG8_LAS unsigned char* lds, const Gemm g, const Sched& S, const Epi& E) {
;     ...
;             const bool last = (t == nt - 2);
;             const char* a1 = cA + (size_t)(t + 1) * kstepA;
;             const char* a2 = last ? nA : cA + (size_t)(t + 2) * kstepA; const char* b2 = last ? nB : cB + (size_t)(t + 2) * kstepB;
;             const char* a3 = a2 + kstepA; const char* b3 = b2 + kstepB;
;             if (last && has_next) S.a_ready(nxt);
;             if constexpr (SP2) {
;             PG8_LDB(B0, 0, 0); PG8_LDB(B1, 0, 1); PG8_SCHED; PG8_LDA(At, 0, 0); PG8_STAGE(PG8_SA(1, 1), a1 + hstepA, voffA);
;             PG8_WAIT_V(8); PG8_WAIT_L(0); PG8_BAR; PG8_MMA(0, 0, At, B0); PG8_MMA(0, 1, At, B1); PG8_BAR; PG8_SCHED;
;             PG8_LDA(At, 0, 1); PG8_STAGE(PG8_SB(0, 0), b2, voffB); PG8_STAGE(PG8_SB(0, 1), b2 + hstepB, voffB); PG8_STAGE(PG8_SA(0, 0), a2, voffA);
;             PG8_WAIT_V(8); PG8_WAIT_L(0); PG8_BAR; PG8_MMA(1, 0, At, B0); PG8_MMA(1, 1, At, B1); PG8_BAR; PG8_SCHED;
.LBB0_185:
	s_add_u32 s13, s20, 0x4000
	s_addc_u32 s22, s21, 0
	s_cmp_eq_u32 vcc_hi, 28
	s_cselect_b32 s26, s70, s13
	s_cselect_b32 s27, s9, s22
	s_cselect_b32 s24, s71, s77
	s_cselect_b32 s25, s7, vcc_lo
	s_add_u32 s22, s26, 0x8000
	s_addc_u32 s23, s27, 0
	s_add_i32 s13, 0, 0x10000
	v_add_u32_e32 v36, s13, v160
	s_add_i32 s88, 0, 0x14000
	ds_read_b128 v[152:155], v36
	ds_read_b128 v[156:159], v36 offset:1024
	ds_read_b128 v[162:165], v36 offset:2048
	ds_read_b128 v[166:169], v36 offset:3072
	ds_read_b128 v[186:189], v161
	ds_read_b128 v[190:193], v161 offset:1024
	v_add_u32_e32 v36, s88, v160
	ds_read_b128 v[170:173], v36
	ds_read_b128 v[174:177], v36 offset:1024
	ds_read_b128 v[178:181], v36 offset:2048
	ds_read_b128 v[182:185], v36 offset:3072
	s_add_i32 m0, s19, 0xc000
	ds_read_b128 v[194:197], v161 offset:2048
	ds_read_b128 v[198:201], v161 offset:3072
	ds_read_b128 v[202:205], v161 offset:4096
	ds_read_b128 v[206:209], v161 offset:5120
	ds_read_b128 v[210:213], v161 offset:6144
	ds_read_b128 v[214:217], v161 offset:7168
	global_load_lds_dwordx4 v148, s[20:21]
	s_add_i32 m0, s19, 0xe000
	s_nop 0
	global_load_lds_dwordx4 v150, s[20:21]
	s_waitcnt vmcnt(8)
	s_waitcnt lgkmcnt(10)
	v_mfma_f32_16x16x32_bf16 v[132:135], v[152:155], v[186:189], v[132:135]
	v_mfma_f32_16x16x32_bf16 v[132:135], v[156:159], v[190:193], v[132:135]
	v_mfma_f32_16x16x32_bf16 v[128:131], v[166:169], v[190:193], v[128:131]
	v_mfma_f32_16x16x32_bf16 v[128:131], v[162:165], v[186:189], v[128:131]
	s_barrier
	s_setprio 1
	s_waitcnt lgkmcnt(0)
	v_mfma_f32_16x16x32_bf16 v[112:115], v[162:165], v[194:197], v[112:115]
	v_mfma_f32_16x16x32_bf16 v[112:115], v[166:169], v[198:201], v[112:115]
	v_mfma_f32_16x16x32_bf16 v[116:119], v[156:159], v[198:201], v[116:119]
	v_mfma_f32_16x16x32_bf16 v[116:119], v[152:155], v[194:197], v[116:119]
	v_mfma_f32_16x16x32_bf16 v[100:103], v[152:155], v[202:205], v[100:103]
	v_mfma_f32_16x16x32_bf16 v[100:103], v[156:159], v[206:209], v[100:103]
	v_mfma_f32_16x16x32_bf16 v[96:99], v[166:169], v[206:209], v[96:99]
	v_mfma_f32_16x16x32_bf16 v[96:99], v[162:165], v[202:205], v[96:99]
	v_mfma_f32_16x16x32_bf16 v[80:83], v[162:165], v[210:213], v[80:83]
	v_mfma_f32_16x16x32_bf16 v[80:83], v[166:169], v[214:217], v[80:83]
	v_mfma_f32_16x16x32_bf16 v[84:87], v[156:159], v[214:217], v[84:87]
	v_mfma_f32_16x16x32_bf16 v[84:87], v[152:155], v[210:213], v[84:87]
	s_setprio 0
	s_setprio 1
	v_mfma_f32_16x16x32_bf16 v[76:79], v[170:173], v[210:213], v[76:79]
	v_mfma_f32_16x16x32_bf16 v[76:79], v[174:177], v[214:217], v[76:79]
	v_mfma_f32_16x16x32_bf16 v[124:127], v[174:177], v[190:193], v[124:127]
	v_mfma_f32_16x16x32_bf16 v[124:127], v[170:173], v[186:189], v[124:127]
	v_mfma_f32_16x16x32_bf16 v[120:123], v[178:181], v[186:189], v[120:123]
	v_mfma_f32_16x16x32_bf16 v[120:123], v[182:185], v[190:193], v[120:123]
	v_mfma_f32_16x16x32_bf16 v[104:107], v[182:185], v[198:201], v[104:107]
	v_mfma_f32_16x16x32_bf16 v[104:107], v[178:181], v[194:197], v[104:107]
	v_mfma_f32_16x16x32_bf16 v[108:111], v[170:173], v[194:197], v[108:111]
	v_mfma_f32_16x16x32_bf16 v[108:111], v[174:177], v[198:201], v[108:111]
	v_mfma_f32_16x16x32_bf16 v[92:95], v[174:177], v[206:209], v[92:95]
	v_mfma_f32_16x16x32_bf16 v[92:95], v[170:173], v[202:205], v[92:95]
	v_mfma_f32_16x16x32_bf16 v[88:91], v[178:181], v[202:205], v[88:91]
	v_mfma_f32_16x16x32_bf16 v[88:91], v[182:185], v[206:209], v[88:91]
	v_mfma_f32_16x16x32_bf16 v[72:75], v[182:185], v[214:217], v[72:75]
	v_mfma_f32_16x16x32_bf16 v[72:75], v[178:181], v[210:213], v[72:75]
	s_setprio 0
	s_barrier
	s_add_i32 s13, s13, s31
	s_mov_b32 m0, s13
	ds_read_b128 v[186:189], v161 offset:16384
	ds_read_b128 v[190:193], v161 offset:17408
	ds_read_b128 v[194:197], v161 offset:18432
	ds_read_b128 v[198:201], v161 offset:19456
	ds_read_b128 v[202:205], v161 offset:20480
	ds_read_b128 v[206:209], v161 offset:21504
	ds_read_b128 v[210:213], v161 offset:22528
	ds_read_b128 v[214:217], v161 offset:23552
	global_load_lds_dwordx4 v140, s[24:25]
	s_add_i32 m0, s13, 0x2000
	s_add_u32 s68, s24, 0x4000
	s_addc_u32 s69, s25, 0
	s_add_i32 s13, s88, s31
	global_load_lds_dwordx4 v136, s[24:25]
	s_mov_b32 m0, s13
	s_nop 0
	global_load_lds_dwordx4 v140, s[68:69]
	s_add_i32 m0, s13, 0x2000
	s_nop 0
	global_load_lds_dwordx4 v136, s[68:69]
	s_mov_b32 m0, s19
	s_nop 0
	global_load_lds_dwordx4 v142, s[26:27]
	s_mov_b32 m0, s35
	s_nop 0
	global_load_lds_dwordx4 v138, s[26:27]
	s_waitcnt vmcnt(8)
	s_waitcnt lgkmcnt(6)
	v_mfma_f32_16x16x32_bf16 v[68:71], v[152:155], v[186:189], v[68:71]
	v_mfma_f32_16x16x32_bf16 v[68:71], v[156:159], v[190:193], v[68:71]
	v_mfma_f32_16x16x32_bf16 v[64:67], v[166:169], v[190:193], v[64:67]
	v_mfma_f32_16x16x32_bf16 v[64:67], v[162:165], v[186:189], v[64:67]
	s_barrier
; #define PG8_STAGE(bufoff, gbase, voff) do { _Pragma("unroll") for (int _i = 0; _i < 2; ++_i) \
;         __builtin_amdgcn_global_load_lds((const unsigned*)((const char*)(gbase) + (voff)[_i]), (PG8_LAS unsigned*)(lds + (bufoff) + ldsw + _i * 8192), 16, 0, 0); } while (0)
; #define PG8_LDA(dst, b, h) do { _Pragma("unroll") for (int m = 0; m < 4; ++m) _Pragma("unroll") for (int k = 0; k < 2; ++k) dst[m][k] = *(const PG8_LAS bf16x8*)(lds + PG8_SA(b, h) + aoff + m * 2048 + k * 1024); } while (0)
; #define PG8_LDB(dst, b, h) do { _Pragma("unroll") for (int n = 0; n < 2; ++n) _Pragma("unroll") for (int k = 0; k < 2; ++k) dst[n][k] = *(const PG8_LAS bf16x8*)(lds + PG8_SB(b, h) + boff + n * 2048 + k * 1024); } while (0)
; #define PG8_MMA(ai, bj, At, Bt) do { __builtin_amdgcn_s_setprio(1); _Pragma("unroll") for (int m = 0; m < 4; ++m) _Pragma("unroll") for (int n = 0; n < 2; ++n) _Pragma("unroll") for (int k = 0; k < 2; ++k) \
;         acc[ai][bj][m][n] = __builtin_amdgcn_mfma_f32_16x16x32_bf16(Bt[n][k], At[m][k], acc[ai][bj][m][n], 0, 0, 0); __builtin_amdgcn_s_setprio(0); } while (0)
; #define PG8_WAIT_V(n) asm volatile("s_waitcnt vmcnt(" #n ")" ::: "memory")
; #define PG8_WAIT_L(n) asm volatile("s_waitcnt lgkmcnt(" #n ")" ::: "memory")
; #define PG8_BAR __builtin_amdgcn_s_barrier()
; #define PG8_SCHED __builtin_amdgcn_sched_barrier(0)
; template <class Epi, class Sched, bool ALIGN_EPI = false, bool SP2 = false, bool ABLK = false, bool BBLK = false>
; __device__ __forceinline__ void gemm_phase(PG8_LAS unsigned char* lds, const Gemm g, const Sched& S, const Epi& E) {
;     ...
;             PG8_WAIT_V(8); PG8_WAIT_L(0); PG8_BAR; PG8_MMA(1, 0, At, B0); PG8_MMA(1, 1, At, B1); PG8_BAR; PG8_SCHED;
;             PG8_LDB(B0, 1, 0); PG8_LDB(B1, 1, 1); PG8_SCHED; PG8_LDA(At, 1, 0); PG8_STAGE(PG8_SA(0, 1), a2 + hstepA, voffA);
;             PG8_WAIT_V(8); PG8_WAIT_L(0); PG8_BAR; PG8_MMA(0, 0, At, B0); PG8_MMA(0, 1, At, B1); PG8_BAR; PG8_SCHED;
	s_setprio 1
	s_waitcnt lgkmcnt(0)
	v_mfma_f32_16x16x32_bf16 v[48:51], v[162:165], v[194:197], v[48:51]
	v_mfma_f32_16x16x32_bf16 v[48:51], v[166:169], v[198:201], v[48:51]
	v_mfma_f32_16x16x32_bf16 v[52:55], v[156:159], v[198:201], v[52:55]
	v_mfma_f32_16x16x32_bf16 v[52:55], v[152:155], v[194:197], v[52:55]
	v_mfma_f32_16x16x32_bf16 v[32:35], v[152:155], v[202:205], v[32:35]
	v_mfma_f32_16x16x32_bf16 v[32:35], v[156:159], v[206:209], v[32:35]
	v_mfma_f32_16x16x32_bf16 v[28:31], v[166:169], v[206:209], v[28:31]
	v_mfma_f32_16x16x32_bf16 v[28:31], v[162:165], v[202:205], v[28:31]
	v_mfma_f32_16x16x32_bf16 v[12:15], v[162:165], v[210:213], v[12:15]
	v_mfma_f32_16x16x32_bf16 v[12:15], v[166:169], v[214:217], v[12:15]
	v_mfma_f32_16x16x32_bf16 v[16:19], v[156:159], v[214:217], v[16:19]
	v_mfma_f32_16x16x32_bf16 v[16:19], v[152:155], v[210:213], v[16:19]
	s_setprio 0
	s_setprio 1
	v_mfma_f32_16x16x32_bf16 v[8:11], v[170:173], v[210:213], v[8:11]
	v_mfma_f32_16x16x32_bf16 v[8:11], v[174:177], v[214:217], v[8:11]
	v_mfma_f32_16x16x32_bf16 v[60:63], v[174:177], v[190:193], v[60:63]
	v_mfma_f32_16x16x32_bf16 v[60:63], v[170:173], v[186:189], v[60:63]
	v_mfma_f32_16x16x32_bf16 v[56:59], v[178:181], v[186:189], v[56:59]
	v_mfma_f32_16x16x32_bf16 v[56:59], v[182:185], v[190:193], v[56:59]
	v_mfma_f32_16x16x32_bf16 v[40:43], v[182:185], v[198:201], v[40:43]
	v_mfma_f32_16x16x32_bf16 v[40:43], v[178:181], v[194:197], v[40:43]
	v_mfma_f32_16x16x32_bf16 v[44:47], v[170:173], v[194:197], v[44:47]
	v_mfma_f32_16x16x32_bf16 v[44:47], v[174:177], v[198:201], v[44:47]
	v_mfma_f32_16x16x32_bf16 v[24:27], v[174:177], v[206:209], v[24:27]
	v_mfma_f32_16x16x32_bf16 v[24:27], v[170:173], v[202:205], v[24:27]
	v_mfma_f32_16x16x32_bf16 v[20:23], v[178:181], v[202:205], v[20:23]
	v_mfma_f32_16x16x32_bf16 v[20:23], v[182:185], v[206:209], v[20:23]
	v_mfma_f32_16x16x32_bf16 v[4:7], v[182:185], v[214:217], v[4:7]
	v_mfma_f32_16x16x32_bf16 v[4:7], v[178:181], v[210:213], v[4:7]
	s_setprio 0
	s_barrier
	s_add_i32 s13, 0, 0x18000
	v_add_u32_e32 v36, s13, v160
	s_add_i32 s68, 0, 0x1c000
	ds_read_b128 v[152:155], v36
	ds_read_b128 v[156:159], v36 offset:1024
	ds_read_b128 v[162:165], v36 offset:2048
	ds_read_b128 v[166:169], v36 offset:3072
	ds_read_b128 v[186:189], v161 offset:32768
	ds_read_b128 v[190:193], v161 offset:33792
	v_add_u32_e32 v36, s68, v160
	ds_read_b128 v[170:173], v36
	ds_read_b128 v[174:177], v36 offset:1024
	ds_read_b128 v[178:181], v36 offset:2048
	ds_read_b128 v[182:185], v36 offset:3072
	s_add_u32 s26, s26, 0x4000
	s_addc_u32 s27, s27, 0
	s_mov_b32 m0, s36
	ds_read_b128 v[194:197], v161 offset:34816
	ds_read_b128 v[198:201], v161 offset:35840
	ds_read_b128 v[202:205], v161 offset:36864
	ds_read_b128 v[206:209], v161 offset:37888
	ds_read_b128 v[210:213], v161 offset:38912
	ds_read_b128 v[214:217], v161 offset:39936
	global_load_lds_dwordx4 v142, s[26:27]
	s_mov_b32 m0, s37
	s_nop 0
	global_load_lds_dwordx4 v138, s[26:27]
	s_waitcnt vmcnt(8)
	s_waitcnt lgkmcnt(10)
	v_mfma_f32_16x16x32_bf16 v[132:135], v[152:155], v[186:189], v[132:135]
	v_mfma_f32_16x16x32_bf16 v[132:135], v[156:159], v[190:193], v[132:135]
	v_mfma_f32_16x16x32_bf16 v[128:131], v[166:169], v[190:193], v[128:131]
	v_mfma_f32_16x16x32_bf16 v[128:131], v[162:165], v[186:189], v[128:131]
	s_barrier
	s_setprio 1
	s_waitcnt lgkmcnt(0)
	v_mfma_f32_16x16x32_bf16 v[112:115], v[162:165], v[194:197], v[112:115]
	v_mfma_f32_16x16x32_bf16 v[112:115], v[166:169], v[198:201], v[112:115]
	v_mfma_f32_16x16x32_bf16 v[116:119], v[156:159], v[198:201], v[116:119]
	v_mfma_f32_16x16x32_bf16 v[116:119], v[152:155], v[194:197], v[116:119]
	v_mfma_f32_16x16x32_bf16 v[100:103], v[152:155], v[202:205], v[100:103]
	v_mfma_f32_16x16x32_bf16 v[100:103], v[156:159], v[206:209], v[100:103]
	v_mfma_f32_16x16x32_bf16 v[96:99], v[166:169], v[206:209], v[96:99]
	v_mfma_f32_16x16x32_bf16 v[96:99], v[162:165], v[202:205], v[96:99]
	v_mfma_f32_16x16x32_bf16 v[80:83], v[162:165], v[210:213], v[80:83]
	v_mfma_f32_16x16x32_bf16 v[80:83], v[166:169], v[214:217], v[80:83]
	v_mfma_f32_16x16x32_bf16 v[84:87], v[156:159], v[214:217], v[84:87]
	v_mfma_f32_16x16x32_bf16 v[84:87], v[152:155], v[210:213], v[84:87]
	s_setprio 0
	s_setprio 1
	v_mfma_f32_16x16x32_bf16 v[76:79], v[170:173], v[210:213], v[76:79]
	v_mfma_f32_16x16x32_bf16 v[76:79], v[174:177], v[214:217], v[76:79]
	v_mfma_f32_16x16x32_bf16 v[124:127], v[174:177], v[190:193], v[124:127]
	v_mfma_f32_16x16x32_bf16 v[124:127], v[170:173], v[186:189], v[124:127]
	v_mfma_f32_16x16x32_bf16 v[120:123], v[178:181], v[186:189], v[120:123]
	v_mfma_f32_16x16x32_bf16 v[120:123], v[182:185], v[190:193], v[120:123]
	v_mfma_f32_16x16x32_bf16 v[104:107], v[182:185], v[198:201], v[104:107]
	v_mfma_f32_16x16x32_bf16 v[104:107], v[178:181], v[194:197], v[104:107]
	v_mfma_f32_16x16x32_bf16 v[108:111], v[170:173], v[194:197], v[108:111]
	v_mfma_f32_16x16x32_bf16 v[108:111], v[174:177], v[198:201], v[108:111]
	v_mfma_f32_16x16x32_bf16 v[92:95], v[174:177], v[206:209], v[92:95]
	v_mfma_f32_16x16x32_bf16 v[92:95], v[170:173], v[202:205], v[92:95]
	v_mfma_f32_16x16x32_bf16 v[88:91], v[178:181], v[202:205], v[88:91]
	v_mfma_f32_16x16x32_bf16 v[88:91], v[182:185], v[206:209], v[88:91]
	v_mfma_f32_16x16x32_bf16 v[72:75], v[182:185], v[214:217], v[72:75]
	v_mfma_f32_16x16x32_bf16 v[72:75], v[178:181], v[210:213], v[72:75]
	s_setprio 0
	s_barrier
; #define PG8_STAGE(bufoff, gbase, voff) do { _Pragma("unroll") for (int _i = 0; _i < 2; ++_i) \
;         __builtin_amdgcn_global_load_lds((const unsigned*)((const char*)(gbase) + (voff)[_i]), (PG8_LAS unsigned*)(lds + (bufoff) + ldsw + _i * 8192), 16, 0, 0); } while (0)
; #define PG8_LDA(dst, b, h) do { _Pragma("unroll") for (int m = 0; m < 4; ++m) _Pragma("unroll") for (int k = 0; k < 2; ++k) dst[m][k] = *(const PG8_LAS bf16x8*)(lds + PG8_SA(b, h) + aoff + m * 2048 + k * 1024); } while (0)
; #define PG8_MMA(ai, bj, At, Bt) do { __builtin_amdgcn_s_setprio(1); _Pragma("unroll") for (int m = 0; m < 4; ++m) _Pragma("unroll") for (int n = 0; n < 2; ++n) _Pragma("unroll") for (int k = 0; k < 2; ++k) \
;         acc[ai][bj][m][n] = __builtin_amdgcn_mfma_f32_16x16x32_bf16(Bt[n][k], At[m][k], acc[ai][bj][m][n], 0, 0, 0); __builtin_amdgcn_s_setprio(0); } while (0)
; #define PG8_WAIT_V(n) asm volatile("s_waitcnt vmcnt(" #n ")" ::: "memory")
; #define PG8_WAIT_L(n) asm volatile("s_waitcnt lgkmcnt(" #n ")" ::: "memory")
; #define PG8_BAR __builtin_amdgcn_s_barrier()
; #define PG8_SCHED __builtin_amdgcn_sched_barrier(0)
; template <class Epi, class Sched, bool ALIGN_EPI = false, bool SP2 = false, bool ABLK = false, bool BBLK = false>
; __device__ __forceinline__ void gemm_phase(PG8_LAS unsigned char* lds, const Gemm g, const Sched& S, const Epi& E) {
;     ...
;             PG8_LDA(At, 1, 1); PG8_STAGE(PG8_SB(1, 0), b3, voffB); PG8_STAGE(PG8_SB(1, 1), b3 + hstepB, voffB); PG8_STAGE(PG8_SA(1, 0), a3, voffA);
;             PG8_WAIT_V(8); PG8_WAIT_L(0); PG8_BAR; PG8_MMA(1, 0, At, B0); PG8_MMA(1, 1, At, B1); PG8_BAR; PG8_SCHED;
	s_add_u32 s26, s24, 0x8000
	s_addc_u32 s27, s25, 0
	s_add_i32 s13, s13, s31
	s_mov_b32 m0, s13
	ds_read_b128 v[186:189], v161 offset:49152
	ds_read_b128 v[190:193], v161 offset:50176
	ds_read_b128 v[194:197], v161 offset:51200
	ds_read_b128 v[198:201], v161 offset:52224
	ds_read_b128 v[202:205], v161 offset:53248
	ds_read_b128 v[206:209], v161 offset:54272
	ds_read_b128 v[210:213], v161 offset:55296
	ds_read_b128 v[214:217], v161 offset:56320
	global_load_lds_dwordx4 v140, s[26:27]
	s_add_i32 m0, s13, 0x2000
	s_add_u32 s24, s24, 0xc000
	s_addc_u32 s25, s25, 0
	s_add_i32 s13, s68, s31
	global_load_lds_dwordx4 v136, s[26:27]
	s_mov_b32 m0, s13
	s_nop 0
	global_load_lds_dwordx4 v140, s[24:25]
	s_add_i32 m0, s13, 0x2000
	s_nop 0
	global_load_lds_dwordx4 v136, s[24:25]
	s_mov_b32 m0, s62
	s_nop 0
	global_load_lds_dwordx4 v142, s[22:23]
	s_mov_b32 m0, s63
	s_nop 0
	global_load_lds_dwordx4 v138, s[22:23]
	s_waitcnt vmcnt(8)
	s_waitcnt lgkmcnt(6)
	v_mfma_f32_16x16x32_bf16 v[68:71], v[152:155], v[186:189], v[68:71]
	v_mfma_f32_16x16x32_bf16 v[68:71], v[156:159], v[190:193], v[68:71]
	v_mfma_f32_16x16x32_bf16 v[64:67], v[166:169], v[190:193], v[64:67]
	v_mfma_f32_16x16x32_bf16 v[64:67], v[162:165], v[186:189], v[64:67]
	s_barrier
	s_setprio 1
	s_waitcnt lgkmcnt(0)
	v_mfma_f32_16x16x32_bf16 v[48:51], v[162:165], v[194:197], v[48:51]
	v_mfma_f32_16x16x32_bf16 v[48:51], v[166:169], v[198:201], v[48:51]
	v_mfma_f32_16x16x32_bf16 v[52:55], v[156:159], v[198:201], v[52:55]
	v_mfma_f32_16x16x32_bf16 v[52:55], v[152:155], v[194:197], v[52:55]
	v_mfma_f32_16x16x32_bf16 v[32:35], v[152:155], v[202:205], v[32:35]
	v_mfma_f32_16x16x32_bf16 v[32:35], v[156:159], v[206:209], v[32:35]
	v_mfma_f32_16x16x32_bf16 v[28:31], v[166:169], v[206:209], v[28:31]
	v_mfma_f32_16x16x32_bf16 v[28:31], v[162:165], v[202:205], v[28:31]
	v_mfma_f32_16x16x32_bf16 v[12:15], v[162:165], v[210:213], v[12:15]
	v_mfma_f32_16x16x32_bf16 v[12:15], v[166:169], v[214:217], v[12:15]
	v_mfma_f32_16x16x32_bf16 v[16:19], v[156:159], v[214:217], v[16:19]
	v_mfma_f32_16x16x32_bf16 v[16:19], v[152:155], v[210:213], v[16:19]
	s_setprio 0
	s_setprio 1
	v_mfma_f32_16x16x32_bf16 v[8:11], v[170:173], v[210:213], v[8:11]
	v_mfma_f32_16x16x32_bf16 v[8:11], v[174:177], v[214:217], v[8:11]
	v_mfma_f32_16x16x32_bf16 v[60:63], v[174:177], v[190:193], v[60:63]
	v_mfma_f32_16x16x32_bf16 v[60:63], v[170:173], v[186:189], v[60:63]
	v_mfma_f32_16x16x32_bf16 v[56:59], v[178:181], v[186:189], v[56:59]
	v_mfma_f32_16x16x32_bf16 v[56:59], v[182:185], v[190:193], v[56:59]
	v_mfma_f32_16x16x32_bf16 v[40:43], v[182:185], v[198:201], v[40:43]
	v_mfma_f32_16x16x32_bf16 v[40:43], v[178:181], v[194:197], v[40:43]
	v_mfma_f32_16x16x32_bf16 v[44:47], v[170:173], v[194:197], v[44:47]
	v_mfma_f32_16x16x32_bf16 v[44:47], v[174:177], v[198:201], v[44:47]
	v_mfma_f32_16x16x32_bf16 v[24:27], v[174:177], v[206:209], v[24:27]
	v_mfma_f32_16x16x32_bf16 v[24:27], v[170:173], v[202:205], v[24:27]
	v_mfma_f32_16x16x32_bf16 v[20:23], v[178:181], v[202:205], v[20:23]
	v_mfma_f32_16x16x32_bf16 v[20:23], v[182:185], v[206:209], v[20:23]
	v_mfma_f32_16x16x32_bf16 v[4:7], v[182:185], v[214:217], v[4:7]
	v_mfma_f32_16x16x32_bf16 v[4:7], v[178:181], v[210:213], v[4:7]
	s_setprio 0
	s_barrier
	s_add_i32 vcc_hi, vcc_hi, 2
	s_add_u32 s20, s20, 0x10000
	s_addc_u32 s21, s21, 0
	s_add_u32 s77, s77, 0x10000
	s_addc_u32 vcc_lo, vcc_lo, 0
	s_cmp_gt_u32 vcc_hi, 29
	s_cbranch_scc0 .LBB0_185
	s_and_b64 vcc, exec, s[4:5]
	s_cbranch_vccz .LBB0_188
	s_barrier

; #define PG8_STAGE(bufoff, gbase, voff) do { _Pragma("unroll") for (int _i = 0; _i < 2; ++_i) \
;         __builtin_amdgcn_global_load_lds((const unsigned*)((const char*)(gbase) + (voff)[_i]), (PG8_LAS unsigned*)(lds + (bufoff) + ldsw + _i * 8192), 16, 0, 0); } while (0)
; #define PG8_LDA(dst, b, h) do { _Pragma("unroll") for (int m = 0; m < 4; ++m) _Pragma("unroll") for (int k = 0; k < 2; ++k) dst[m][k] = *(const PG8_LAS bf16x8*)(lds + PG8_SA(b, h) + aoff + m * 2048 + k * 1024); } while (0)
; #define PG8_LDB(dst, b, h) do { _Pragma("unroll") for (int n = 0; n < 2; ++n) _Pragma("unroll") for (int k = 0; k < 2; ++k) dst[n][k] = *(const PG8_LAS bf16x8*)(lds + PG8_SB(b, h) + boff + n * 2048 + k * 1024); } while (0)
; #define PG8_MMA(ai, bj, At, Bt) do { __builtin_amdgcn_s_setprio(1); _Pragma("unroll") for (int m = 0; m < 4; ++m) _Pragma("unroll") for (int n = 0; n < 2; ++n) _Pragma("unroll") for (int k = 0; k < 2; ++k) \
;         acc[ai][bj][m][n] = __builtin_amdgcn_mfma_f32_16x16x32_bf16(Bt[n][k], At[m][k], acc[ai][bj][m][n], 0, 0, 0); __builtin_amdgcn_s_setprio(0); } while (0)
; #define PG8_WAIT_V(n) asm volatile("s_waitcnt vmcnt(" #n ")" ::: "memory")
; #define PG8_BAR __builtin_amdgcn_s_barrier()
; template <class Epi, class Sched, bool ALIGN_EPI = false, bool SP2 = false, bool ABLK = false, bool BBLK = false>
; __device__ __forceinline__ void gemm_phase(PG8_LAS unsigned char* lds, const Gemm g, const Sched& S, const Epi& E) {
;     ...
;             const bool last = (t == nt - 2);
;             const char* a1 = cA + (size_t)(t + 1) * kstepA;
;             const char* a2 = last ? nA : cA + (size_t)(t + 2) * kstepA; const char* b2 = last ? nB : cB + (size_t)(t + 2) * kstepB;
;             const char* a3 = a2 + kstepA; const char* b3 = b2 + kstepB;
;             if (last && has_next) S.a_ready(nxt);
;             if constexpr (SP2) {
;             PG8_LDB(B0, 0, 0); PG8_LDB(B1, 0, 1); PG8_SCHED; PG8_LDA(At, 0, 0); PG8_STAGE(PG8_SA(1, 1), a1 + hstepA, voffA);
;             PG8_WAIT_V(8); PG8_WAIT_L(0); PG8_BAR; PG8_MMA(0, 0, At, B0); PG8_MMA(0, 1, At, B1); PG8_BAR; PG8_SCHED;
;             PG8_LDA(At, 0, 1); PG8_STAGE(PG8_SB(0, 0), b2, voffB); PG8_STAGE(PG8_SB(0, 1), b2 + hstepB, voffB); PG8_STAGE(PG8_SA(0, 0), a2, voffA);
;             PG8_WAIT_V(8); PG8_WAIT_L(0); PG8_BAR; PG8_MMA(1, 0, At, B0); PG8_MMA(1, 1, At, B1); PG8_BAR; PG8_SCHED;
.LBB0_439:
	s_add_u32 s16, s10, 0x4000
	s_addc_u32 s17, s11, 0
	s_cmpk_eq_i32 s13, 0x54
	s_cselect_b32 s20, s0, s16
	s_cselect_b32 s21, s1, s17
	s_cselect_b32 s18, s8, vcc_lo
	s_cselect_b32 s19, s9, vcc_hi
	s_add_u32 s16, s20, 0x8000
	s_addc_u32 s17, s21, 0
	s_add_i32 s68, 0, 0x10000
	v_add_u32_e32 v36, s68, v148
	s_add_i32 s88, 0, 0x14000
	ds_read_b128 v[152:155], v36
	ds_read_b128 v[156:159], v36 offset:1024
	ds_read_b128 v[160:163], v36 offset:2048
	ds_read_b128 v[164:167], v36 offset:3072
	ds_read_b128 v[184:187], v150
	ds_read_b128 v[188:191], v150 offset:1024
	v_add_u32_e32 v36, s88, v148
	ds_read_b128 v[168:171], v36
	ds_read_b128 v[172:175], v36 offset:1024
	ds_read_b128 v[176:179], v36 offset:2048
	ds_read_b128 v[180:183], v36 offset:3072
	s_add_i32 m0, s27, 0xc000
	ds_read_b128 v[192:195], v150 offset:2048
	ds_read_b128 v[196:199], v150 offset:3072
	ds_read_b128 v[200:203], v150 offset:4096
	ds_read_b128 v[204:207], v150 offset:5120
	ds_read_b128 v[208:211], v150 offset:6144
	ds_read_b128 v[212:215], v150 offset:7168
	global_load_lds_dwordx4 v144, s[10:11]
	s_add_i32 m0, s27, 0xe000
	s_nop 0
	global_load_lds_dwordx4 v146, s[10:11]
	s_waitcnt vmcnt(8)
	s_waitcnt lgkmcnt(10)
	v_mfma_f32_16x16x32_bf16 v[132:135], v[152:155], v[184:187], v[132:135]
	v_mfma_f32_16x16x32_bf16 v[132:135], v[156:159], v[188:191], v[132:135]
	v_mfma_f32_16x16x32_bf16 v[128:131], v[164:167], v[188:191], v[128:131]
	v_mfma_f32_16x16x32_bf16 v[128:131], v[160:163], v[184:187], v[128:131]
	s_barrier
	s_setprio 1
	s_waitcnt lgkmcnt(0)
	v_mfma_f32_16x16x32_bf16 v[120:123], v[160:163], v[192:195], v[120:123]
	v_mfma_f32_16x16x32_bf16 v[120:123], v[164:167], v[196:199], v[120:123]
	v_mfma_f32_16x16x32_bf16 v[124:127], v[156:159], v[196:199], v[124:127]
	v_mfma_f32_16x16x32_bf16 v[124:127], v[152:155], v[192:195], v[124:127]
	v_mfma_f32_16x16x32_bf16 v[108:111], v[152:155], v[200:203], v[108:111]
	v_mfma_f32_16x16x32_bf16 v[108:111], v[156:159], v[204:207], v[108:111]
	v_mfma_f32_16x16x32_bf16 v[104:107], v[164:167], v[204:207], v[104:107]
	v_mfma_f32_16x16x32_bf16 v[104:107], v[160:163], v[200:203], v[104:107]
	v_mfma_f32_16x16x32_bf16 v[88:91], v[160:163], v[208:211], v[88:91]
	v_mfma_f32_16x16x32_bf16 v[88:91], v[164:167], v[212:215], v[88:91]
	v_mfma_f32_16x16x32_bf16 v[92:95], v[156:159], v[212:215], v[92:95]
	v_mfma_f32_16x16x32_bf16 v[92:95], v[152:155], v[208:211], v[92:95]
	s_setprio 0
	s_setprio 1
	v_mfma_f32_16x16x32_bf16 v[76:79], v[168:171], v[208:211], v[76:79]
	v_mfma_f32_16x16x32_bf16 v[76:79], v[172:175], v[212:215], v[76:79]
	v_mfma_f32_16x16x32_bf16 v[116:119], v[172:175], v[188:191], v[116:119]
	v_mfma_f32_16x16x32_bf16 v[116:119], v[168:171], v[184:187], v[116:119]
	v_mfma_f32_16x16x32_bf16 v[112:115], v[176:179], v[184:187], v[112:115]
	v_mfma_f32_16x16x32_bf16 v[112:115], v[180:183], v[188:191], v[112:115]
	v_mfma_f32_16x16x32_bf16 v[96:99], v[180:183], v[196:199], v[96:99]
	v_mfma_f32_16x16x32_bf16 v[96:99], v[176:179], v[192:195], v[96:99]
	v_mfma_f32_16x16x32_bf16 v[100:103], v[168:171], v[192:195], v[100:103]
	v_mfma_f32_16x16x32_bf16 v[100:103], v[172:175], v[196:199], v[100:103]
	v_mfma_f32_16x16x32_bf16 v[84:87], v[172:175], v[204:207], v[84:87]
	v_mfma_f32_16x16x32_bf16 v[84:87], v[168:171], v[200:203], v[84:87]
	v_mfma_f32_16x16x32_bf16 v[80:83], v[176:179], v[200:203], v[80:83]
	v_mfma_f32_16x16x32_bf16 v[80:83], v[180:183], v[204:207], v[80:83]
	v_mfma_f32_16x16x32_bf16 v[72:75], v[180:183], v[212:215], v[72:75]
	v_mfma_f32_16x16x32_bf16 v[72:75], v[176:179], v[208:211], v[72:75]
	s_setprio 0
	s_barrier
	s_add_i32 s68, s68, s24
	s_mov_b32 m0, s68
	ds_read_b128 v[184:187], v150 offset:16384
	ds_read_b128 v[188:191], v150 offset:17408
	ds_read_b128 v[192:195], v150 offset:18432
	ds_read_b128 v[196:199], v150 offset:19456
	ds_read_b128 v[200:203], v150 offset:20480
	ds_read_b128 v[204:207], v150 offset:21504
	ds_read_b128 v[208:211], v150 offset:22528
	ds_read_b128 v[212:215], v150 offset:23552
	global_load_lds_dwordx4 v138, s[18:19]
	s_add_i32 m0, s68, 0x2000
	s_add_u32 s68, s18, 0x4000
	s_addc_u32 s69, s19, 0
	s_add_i32 s88, s88, s24
	global_load_lds_dwordx4 v142, s[18:19]
	s_mov_b32 m0, s88
	s_nop 0
	global_load_lds_dwordx4 v138, s[68:69]
	s_add_i32 m0, s88, 0x2000
	s_nop 0
	global_load_lds_dwordx4 v142, s[68:69]
	s_mov_b32 m0, s27
	s_nop 0
	global_load_lds_dwordx4 v136, s[20:21]
	s_mov_b32 m0, s28
	s_nop 0
	global_load_lds_dwordx4 v140, s[20:21]
	s_waitcnt vmcnt(8)
	s_waitcnt lgkmcnt(6)
	v_mfma_f32_16x16x32_bf16 v[68:71], v[152:155], v[184:187], v[68:71]
	v_mfma_f32_16x16x32_bf16 v[68:71], v[156:159], v[188:191], v[68:71]
	v_mfma_f32_16x16x32_bf16 v[64:67], v[164:167], v[188:191], v[64:67]
	v_mfma_f32_16x16x32_bf16 v[64:67], v[160:163], v[184:187], v[64:67]
	s_barrier
; #define PG8_STAGE(bufoff, gbase, voff) do { _Pragma("unroll") for (int _i = 0; _i < 2; ++_i) \
;         __builtin_amdgcn_global_load_lds((const unsigned*)((const char*)(gbase) + (voff)[_i]), (PG8_LAS unsigned*)(lds + (bufoff) + ldsw + _i * 8192), 16, 0, 0); } while (0)
; #define PG8_LDA(dst, b, h) do { _Pragma("unroll") for (int m = 0; m < 4; ++m) _Pragma("unroll") for (int k = 0; k < 2; ++k) dst[m][k] = *(const PG8_LAS bf16x8*)(lds + PG8_SA(b, h) + aoff + m * 2048 + k * 1024); } while (0)
; #define PG8_LDB(dst, b, h) do { _Pragma("unroll") for (int n = 0; n < 2; ++n) _Pragma("unroll") for (int k = 0; k < 2; ++k) dst[n][k] = *(const PG8_LAS bf16x8*)(lds + PG8_SB(b, h) + boff + n * 2048 + k * 1024); } while (0)
; #define PG8_MMA(ai, bj, At, Bt) do { __builtin_amdgcn_s_setprio(1); _Pragma("unroll") for (int m = 0; m < 4; ++m) _Pragma("unroll") for (int n = 0; n < 2; ++n) _Pragma("unroll") for (int k = 0; k < 2; ++k) \
;         acc[ai][bj][m][n] = __builtin_amdgcn_mfma_f32_16x16x32_bf16(Bt[n][k], At[m][k], acc[ai][bj][m][n], 0, 0, 0); __builtin_amdgcn_s_setprio(0); } while (0)
; #define PG8_WAIT_V(n) asm volatile("s_waitcnt vmcnt(" #n ")" ::: "memory")
; #define PG8_WAIT_L(n) asm volatile("s_waitcnt lgkmcnt(" #n ")" ::: "memory")
; #define PG8_BAR __builtin_amdgcn_s_barrier()
; #define PG8_SCHED __builtin_amdgcn_sched_barrier(0)
; template <class Epi, class Sched, bool ALIGN_EPI = false, bool SP2 = false, bool ABLK = false, bool BBLK = false>
; __device__ __forceinline__ void gemm_phase(PG8_LAS unsigned char* lds, const Gemm g, const Sched& S, const Epi& E) {
;     ...
;             PG8_WAIT_V(8); PG8_WAIT_L(0); PG8_BAR; PG8_MMA(1, 0, At, B0); PG8_MMA(1, 1, At, B1); PG8_BAR; PG8_SCHED;
;             PG8_LDB(B0, 1, 0); PG8_LDB(B1, 1, 1); PG8_SCHED; PG8_LDA(At, 1, 0); PG8_STAGE(PG8_SA(0, 1), a2 + hstepA, voffA);
;             PG8_WAIT_V(8); PG8_WAIT_L(0); PG8_BAR; PG8_MMA(0, 0, At, B0); PG8_MMA(0, 1, At, B1); PG8_BAR; PG8_SCHED;
	s_setprio 1
	s_waitcnt lgkmcnt(0)
	v_mfma_f32_16x16x32_bf16 v[56:59], v[160:163], v[192:195], v[56:59]
	v_mfma_f32_16x16x32_bf16 v[56:59], v[164:167], v[196:199], v[56:59]
	v_mfma_f32_16x16x32_bf16 v[60:63], v[156:159], v[196:199], v[60:63]
	v_mfma_f32_16x16x32_bf16 v[60:63], v[152:155], v[192:195], v[60:63]
	v_mfma_f32_16x16x32_bf16 v[44:47], v[152:155], v[200:203], v[44:47]
	v_mfma_f32_16x16x32_bf16 v[44:47], v[156:159], v[204:207], v[44:47]
	v_mfma_f32_16x16x32_bf16 v[40:43], v[164:167], v[204:207], v[40:43]
	v_mfma_f32_16x16x32_bf16 v[40:43], v[160:163], v[200:203], v[40:43]
	v_mfma_f32_16x16x32_bf16 v[20:23], v[160:163], v[208:211], v[20:23]
	v_mfma_f32_16x16x32_bf16 v[20:23], v[164:167], v[212:215], v[20:23]
	v_mfma_f32_16x16x32_bf16 v[24:27], v[156:159], v[212:215], v[24:27]
	v_mfma_f32_16x16x32_bf16 v[24:27], v[152:155], v[208:211], v[24:27]
	s_setprio 0
	s_setprio 1
	v_mfma_f32_16x16x32_bf16 v[8:11], v[168:171], v[208:211], v[8:11]
	v_mfma_f32_16x16x32_bf16 v[8:11], v[172:175], v[212:215], v[8:11]
	v_mfma_f32_16x16x32_bf16 v[52:55], v[172:175], v[188:191], v[52:55]
	v_mfma_f32_16x16x32_bf16 v[52:55], v[168:171], v[184:187], v[52:55]
	v_mfma_f32_16x16x32_bf16 v[48:51], v[176:179], v[184:187], v[48:51]
	v_mfma_f32_16x16x32_bf16 v[48:51], v[180:183], v[188:191], v[48:51]
	v_mfma_f32_16x16x32_bf16 v[28:31], v[180:183], v[196:199], v[28:31]
	v_mfma_f32_16x16x32_bf16 v[28:31], v[176:179], v[192:195], v[28:31]
	v_mfma_f32_16x16x32_bf16 v[32:35], v[168:171], v[192:195], v[32:35]
	v_mfma_f32_16x16x32_bf16 v[32:35], v[172:175], v[196:199], v[32:35]
	v_mfma_f32_16x16x32_bf16 v[16:19], v[172:175], v[204:207], v[16:19]
	v_mfma_f32_16x16x32_bf16 v[16:19], v[168:171], v[200:203], v[16:19]
	v_mfma_f32_16x16x32_bf16 v[12:15], v[176:179], v[200:203], v[12:15]
	v_mfma_f32_16x16x32_bf16 v[12:15], v[180:183], v[204:207], v[12:15]
	v_mfma_f32_16x16x32_bf16 v[4:7], v[180:183], v[212:215], v[4:7]
	v_mfma_f32_16x16x32_bf16 v[4:7], v[176:179], v[208:211], v[4:7]
	s_setprio 0
	s_barrier
	s_add_i32 s68, 0, 0x18000
	v_add_u32_e32 v36, s68, v148
	s_add_i32 s69, 0, 0x1c000
	ds_read_b128 v[152:155], v36
	ds_read_b128 v[156:159], v36 offset:1024
	ds_read_b128 v[160:163], v36 offset:2048
	ds_read_b128 v[164:167], v36 offset:3072
	ds_read_b128 v[184:187], v150 offset:32768
	ds_read_b128 v[188:191], v150 offset:33792
	v_add_u32_e32 v36, s69, v148
	ds_read_b128 v[168:171], v36
	ds_read_b128 v[172:175], v36 offset:1024
	ds_read_b128 v[176:179], v36 offset:2048
	ds_read_b128 v[180:183], v36 offset:3072
	s_add_u32 s20, s20, 0x4000
	s_addc_u32 s21, s21, 0
	s_mov_b32 m0, s29
	ds_read_b128 v[192:195], v150 offset:34816
	ds_read_b128 v[196:199], v150 offset:35840
	ds_read_b128 v[200:203], v150 offset:36864
	ds_read_b128 v[204:207], v150 offset:37888
	ds_read_b128 v[208:211], v150 offset:38912
	ds_read_b128 v[212:215], v150 offset:39936
	global_load_lds_dwordx4 v136, s[20:21]
	s_mov_b32 m0, s30
	s_nop 0
	global_load_lds_dwordx4 v140, s[20:21]
	s_waitcnt vmcnt(8)
	s_waitcnt lgkmcnt(10)
	v_mfma_f32_16x16x32_bf16 v[132:135], v[152:155], v[184:187], v[132:135]
	v_mfma_f32_16x16x32_bf16 v[132:135], v[156:159], v[188:191], v[132:135]
	v_mfma_f32_16x16x32_bf16 v[128:131], v[164:167], v[188:191], v[128:131]
	v_mfma_f32_16x16x32_bf16 v[128:131], v[160:163], v[184:187], v[128:131]
	s_barrier
	s_setprio 1
	s_waitcnt lgkmcnt(0)
	v_mfma_f32_16x16x32_bf16 v[120:123], v[160:163], v[192:195], v[120:123]
	v_mfma_f32_16x16x32_bf16 v[120:123], v[164:167], v[196:199], v[120:123]
	v_mfma_f32_16x16x32_bf16 v[124:127], v[156:159], v[196:199], v[124:127]
	v_mfma_f32_16x16x32_bf16 v[124:127], v[152:155], v[192:195], v[124:127]
	v_mfma_f32_16x16x32_bf16 v[108:111], v[152:155], v[200:203], v[108:111]
	v_mfma_f32_16x16x32_bf16 v[108:111], v[156:159], v[204:207], v[108:111]
	v_mfma_f32_16x16x32_bf16 v[104:107], v[164:167], v[204:207], v[104:107]
	v_mfma_f32_16x16x32_bf16 v[104:107], v[160:163], v[200:203], v[104:107]
	v_mfma_f32_16x16x32_bf16 v[88:91], v[160:163], v[208:211], v[88:91]
	v_mfma_f32_16x16x32_bf16 v[88:91], v[164:167], v[212:215], v[88:91]
	v_mfma_f32_16x16x32_bf16 v[92:95], v[156:159], v[212:215], v[92:95]
	v_mfma_f32_16x16x32_bf16 v[92:95], v[152:155], v[208:211], v[92:95]
	s_setprio 0
	s_setprio 1
	v_mfma_f32_16x16x32_bf16 v[76:79], v[168:171], v[208:211], v[76:79]
	v_mfma_f32_16x16x32_bf16 v[76:79], v[172:175], v[212:215], v[76:79]
	v_mfma_f32_16x16x32_bf16 v[116:119], v[172:175], v[188:191], v[116:119]
	v_mfma_f32_16x16x32_bf16 v[116:119], v[168:171], v[184:187], v[116:119]
	v_mfma_f32_16x16x32_bf16 v[112:115], v[176:179], v[184:187], v[112:115]
	v_mfma_f32_16x16x32_bf16 v[112:115], v[180:183], v[188:191], v[112:115]
	v_mfma_f32_16x16x32_bf16 v[96:99], v[180:183], v[196:199], v[96:99]
	v_mfma_f32_16x16x32_bf16 v[96:99], v[176:179], v[192:195], v[96:99]
	v_mfma_f32_16x16x32_bf16 v[100:103], v[168:171], v[192:195], v[100:103]
	v_mfma_f32_16x16x32_bf16 v[100:103], v[172:175], v[196:199], v[100:103]
	v_mfma_f32_16x16x32_bf16 v[84:87], v[172:175], v[204:207], v[84:87]
	v_mfma_f32_16x16x32_bf16 v[84:87], v[168:171], v[200:203], v[84:87]
	v_mfma_f32_16x16x32_bf16 v[80:83], v[176:179], v[200:203], v[80:83]
	v_mfma_f32_16x16x32_bf16 v[80:83], v[180:183], v[204:207], v[80:83]
	v_mfma_f32_16x16x32_bf16 v[72:75], v[180:183], v[212:215], v[72:75]
	v_mfma_f32_16x16x32_bf16 v[72:75], v[176:179], v[208:211], v[72:75]
	s_setprio 0
	s_barrier
; #define PG8_STAGE(bufoff, gbase, voff) do { _Pragma("unroll") for (int _i = 0; _i < 2; ++_i) \
;         __builtin_amdgcn_global_load_lds((const unsigned*)((const char*)(gbase) + (voff)[_i]), (PG8_LAS unsigned*)(lds + (bufoff) + ldsw + _i * 8192), 16, 0, 0); } while (0)
; #define PG8_LDA(dst, b, h) do { _Pragma("unroll") for (int m = 0; m < 4; ++m) _Pragma("unroll") for (int k = 0; k < 2; ++k) dst[m][k] = *(const PG8_LAS bf16x8*)(lds + PG8_SA(b, h) + aoff + m * 2048 + k * 1024); } while (0)
; #define PG8_MMA(ai, bj, At, Bt) do { __builtin_amdgcn_s_setprio(1); _Pragma("unroll") for (int m = 0; m < 4; ++m) _Pragma("unroll") for (int n = 0; n < 2; ++n) _Pragma("unroll") for (int k = 0; k < 2; ++k) \
;         acc[ai][bj][m][n] = __builtin_amdgcn_mfma_f32_16x16x32_bf16(Bt[n][k], At[m][k], acc[ai][bj][m][n], 0, 0, 0); __builtin_amdgcn_s_setprio(0); } while (0)
; #define PG8_WAIT_V(n) asm volatile("s_waitcnt vmcnt(" #n ")" ::: "memory")
; #define PG8_WAIT_L(n) asm volatile("s_waitcnt lgkmcnt(" #n ")" ::: "memory")
; #define PG8_BAR __builtin_amdgcn_s_barrier()
; #define PG8_SCHED __builtin_amdgcn_sched_barrier(0)
; template <class Epi, class Sched, bool ALIGN_EPI = false, bool SP2 = false, bool ABLK = false, bool BBLK = false>
; __device__ __forceinline__ void gemm_phase(PG8_LAS unsigned char* lds, const Gemm g, const Sched& S, const Epi& E) {
;     ...
;             PG8_LDA(At, 1, 1); PG8_STAGE(PG8_SB(1, 0), b3, voffB); PG8_STAGE(PG8_SB(1, 1), b3 + hstepB, voffB); PG8_STAGE(PG8_SA(1, 0), a3, voffA);
;             PG8_WAIT_V(8); PG8_WAIT_L(0); PG8_BAR; PG8_MMA(1, 0, At, B0); PG8_MMA(1, 1, At, B1); PG8_BAR; PG8_SCHED;
	s_add_u32 s20, s18, 0x8000
	s_addc_u32 s21, s19, 0
	s_add_i32 s68, s68, s24
	s_mov_b32 m0, s68
	ds_read_b128 v[184:187], v150 offset:49152
	ds_read_b128 v[188:191], v150 offset:50176
	ds_read_b128 v[192:195], v150 offset:51200
	ds_read_b128 v[196:199], v150 offset:52224
	ds_read_b128 v[200:203], v150 offset:53248
	ds_read_b128 v[204:207], v150 offset:54272
	ds_read_b128 v[208:211], v150 offset:55296
	ds_read_b128 v[212:215], v150 offset:56320
	global_load_lds_dwordx4 v138, s[20:21]
	s_add_i32 m0, s68, 0x2000
	s_add_u32 s18, s18, 0xc000
	s_addc_u32 s19, s19, 0
	global_load_lds_dwordx4 v142, s[20:21]
	s_add_i32 s20, s69, s24
	s_mov_b32 m0, s20
	s_nop 0
	global_load_lds_dwordx4 v138, s[18:19]
	s_add_i32 m0, s20, 0x2000
	s_nop 0
	global_load_lds_dwordx4 v142, s[18:19]
	s_mov_b32 m0, s35
	s_nop 0
	global_load_lds_dwordx4 v136, s[16:17]
	s_mov_b32 m0, s70
	s_nop 0
	global_load_lds_dwordx4 v140, s[16:17]
	s_waitcnt vmcnt(8)
	s_waitcnt lgkmcnt(6)
	v_mfma_f32_16x16x32_bf16 v[68:71], v[152:155], v[184:187], v[68:71]
	v_mfma_f32_16x16x32_bf16 v[68:71], v[156:159], v[188:191], v[68:71]
	v_mfma_f32_16x16x32_bf16 v[64:67], v[164:167], v[188:191], v[64:67]
	v_mfma_f32_16x16x32_bf16 v[64:67], v[160:163], v[184:187], v[64:67]
	s_barrier
	s_setprio 1
	s_waitcnt lgkmcnt(0)
	v_mfma_f32_16x16x32_bf16 v[56:59], v[160:163], v[192:195], v[56:59]
	v_mfma_f32_16x16x32_bf16 v[56:59], v[164:167], v[196:199], v[56:59]
	v_mfma_f32_16x16x32_bf16 v[60:63], v[156:159], v[196:199], v[60:63]
	v_mfma_f32_16x16x32_bf16 v[60:63], v[152:155], v[192:195], v[60:63]
	v_mfma_f32_16x16x32_bf16 v[44:47], v[152:155], v[200:203], v[44:47]
	v_mfma_f32_16x16x32_bf16 v[44:47], v[156:159], v[204:207], v[44:47]
	v_mfma_f32_16x16x32_bf16 v[40:43], v[164:167], v[204:207], v[40:43]
	v_mfma_f32_16x16x32_bf16 v[40:43], v[160:163], v[200:203], v[40:43]
	v_mfma_f32_16x16x32_bf16 v[20:23], v[160:163], v[208:211], v[20:23]
	v_mfma_f32_16x16x32_bf16 v[20:23], v[164:167], v[212:215], v[20:23]
	v_mfma_f32_16x16x32_bf16 v[24:27], v[156:159], v[212:215], v[24:27]
	v_mfma_f32_16x16x32_bf16 v[24:27], v[152:155], v[208:211], v[24:27]
	s_setprio 0
	s_setprio 1
	v_mfma_f32_16x16x32_bf16 v[8:11], v[168:171], v[208:211], v[8:11]
	v_mfma_f32_16x16x32_bf16 v[8:11], v[172:175], v[212:215], v[8:11]
	v_mfma_f32_16x16x32_bf16 v[52:55], v[172:175], v[188:191], v[52:55]
	v_mfma_f32_16x16x32_bf16 v[52:55], v[168:171], v[184:187], v[52:55]
	v_mfma_f32_16x16x32_bf16 v[48:51], v[176:179], v[184:187], v[48:51]
	v_mfma_f32_16x16x32_bf16 v[48:51], v[180:183], v[188:191], v[48:51]
	v_mfma_f32_16x16x32_bf16 v[28:31], v[180:183], v[196:199], v[28:31]
	v_mfma_f32_16x16x32_bf16 v[28:31], v[176:179], v[192:195], v[28:31]
	v_mfma_f32_16x16x32_bf16 v[32:35], v[168:171], v[192:195], v[32:35]
	v_mfma_f32_16x16x32_bf16 v[32:35], v[172:175], v[196:199], v[32:35]
	v_mfma_f32_16x16x32_bf16 v[16:19], v[172:175], v[204:207], v[16:19]
	v_mfma_f32_16x16x32_bf16 v[16:19], v[168:171], v[200:203], v[16:19]
	v_mfma_f32_16x16x32_bf16 v[12:15], v[176:179], v[200:203], v[12:15]
	v_mfma_f32_16x16x32_bf16 v[12:15], v[180:183], v[204:207], v[12:15]
	v_mfma_f32_16x16x32_bf16 v[4:7], v[180:183], v[212:215], v[4:7]
	v_mfma_f32_16x16x32_bf16 v[4:7], v[176:179], v[208:211], v[4:7]
	s_setprio 0
	s_barrier
	s_add_i32 s13, s13, 2
	s_add_u32 s10, s10, 0x10000
	s_addc_u32 s11, s11, 0
	s_add_u32 vcc_lo, vcc_lo, 0x10000
	s_addc_u32 vcc_hi, vcc_hi, 0
	s_cmpk_gt_u32 s13, 0x55
	s_cbranch_scc0 .LBB0_439
	s_and_b64 vcc, exec, s[6:7]
	s_cbranch_vccz .LBB0_442
	s_barrier

; #define PG8_STAGE(bufoff, gbase, voff) do { _Pragma("unroll") for (int _i = 0; _i < 2; ++_i) \
;         __builtin_amdgcn_global_load_lds((const unsigned*)((const char*)(gbase) + (voff)[_i]), (PG8_LAS unsigned*)(lds + (bufoff) + ldsw + _i * 8192), 16, 0, 0); } while (0)
; #define PG8_LDA(dst, b, h) do { _Pragma("unroll") for (int m = 0; m < 4; ++m) _Pragma("unroll") for (int k = 0; k < 2; ++k) dst[m][k] = *(const PG8_LAS bf16x8*)(lds + PG8_SA(b, h) + aoff + m * 2048 + k * 1024); } while (0)
; #define PG8_LDB(dst, b, h) do { _Pragma("unroll") for (int n = 0; n < 2; ++n) _Pragma("unroll") for (int k = 0; k < 2; ++k) dst[n][k] = *(const PG8_LAS bf16x8*)(lds + PG8_SB(b, h) + boff + n * 2048 + k * 1024); } while (0)
; #define PG8_MMA(ai, bj, At, Bt) do { __builtin_amdgcn_s_setprio(1); _Pragma("unroll") for (int m = 0; m < 4; ++m) _Pragma("unroll") for (int n = 0; n < 2; ++n) _Pragma("unroll") for (int k = 0; k < 2; ++k) \
;         acc[ai][bj][m][n] = __builtin_amdgcn_mfma_f32_16x16x32_bf16(Bt[n][k], At[m][k], acc[ai][bj][m][n], 0, 0, 0); __builtin_amdgcn_s_setprio(0); } while (0)
; #define PG8_WAIT_V(n) asm volatile("s_waitcnt vmcnt(" #n ")" ::: "memory")
; #define PG8_BAR __builtin_amdgcn_s_barrier()
; template <class Epi, class Sched, bool ALIGN_EPI = false, bool SP2 = false, bool ABLK = false, bool BBLK = false>
; __device__ __forceinline__ void gemm_phase(PG8_LAS unsigned char* lds, const Gemm g, const Sched& S, const Epi& E) {
;     ...
;             const bool last = (t == nt - 2);
;             const char* a1 = cA + (size_t)(t + 1) * kstepA;
;             const char* a2 = last ? nA : cA + (size_t)(t + 2) * kstepA; const char* b2 = last ? nB : cB + (size_t)(t + 2) * kstepB;
;             const char* a3 = a2 + kstepA; const char* b3 = b2 + kstepB;
;             if (last && has_next) S.a_ready(nxt);
;             if constexpr (SP2) {
;             PG8_LDB(B0, 0, 0); PG8_LDB(B1, 0, 1); PG8_SCHED; PG8_LDA(At, 0, 0); PG8_STAGE(PG8_SA(1, 1), a1 + hstepA, voffA);
;             PG8_WAIT_V(8); PG8_WAIT_L(0); PG8_BAR; PG8_MMA(0, 0, At, B0); PG8_MMA(0, 1, At, B1); PG8_BAR; PG8_SCHED;
;             PG8_LDA(At, 0, 1); PG8_STAGE(PG8_SB(0, 0), b2, voffB); PG8_STAGE(PG8_SB(0, 1), b2 + hstepB, voffB); PG8_STAGE(PG8_SA(0, 0), a2, voffA);
;             PG8_WAIT_V(8); PG8_WAIT_L(0); PG8_BAR; PG8_MMA(1, 0, At, B0); PG8_MMA(1, 1, At, B1); PG8_BAR; PG8_SCHED;
.LBB0_916:
	s_add_u32 s22, s20, 0x4000
	s_addc_u32 s23, s21, 0
	s_cmp_eq_u32 s13, 28
	s_cselect_b32 s26, s19, s22
	s_cselect_b32 s27, s1, s23
	s_cselect_b32 s24, s65, s70
	s_cselect_b32 s25, s9, s71
	s_add_u32 s22, s26, 0x8000
	s_addc_u32 s23, s27, 0
	s_add_i32 s68, 0, 0x10000
	v_add_u32_e32 v36, s68, v155
	s_add_i32 s77, 0, 0x14000
	ds_read_b128 v[150:153], v36
	ds_read_b128 v[158:161], v36 offset:1024
	ds_read_b128 v[162:165], v36 offset:2048
	ds_read_b128 v[166:169], v36 offset:3072
	ds_read_b128 v[186:189], v157
	ds_read_b128 v[190:193], v157 offset:1024
	v_add_u32_e32 v36, s77, v155
	ds_read_b128 v[170:173], v36
	ds_read_b128 v[174:177], v36 offset:1024
	ds_read_b128 v[178:181], v36 offset:2048
	ds_read_b128 v[182:185], v36 offset:3072
	s_add_i32 m0, s31, 0xc000
	ds_read_b128 v[194:197], v157 offset:2048
	ds_read_b128 v[198:201], v157 offset:3072
	ds_read_b128 v[202:205], v157 offset:4096
	ds_read_b128 v[206:209], v157 offset:5120
	ds_read_b128 v[210:213], v157 offset:6144
	ds_read_b128 v[214:217], v157 offset:7168
	global_load_lds_dwordx4 v146, s[20:21]
	s_add_i32 m0, s31, 0xe000
	s_nop 0
	global_load_lds_dwordx4 v148, s[20:21]
	s_waitcnt vmcnt(8)
	s_waitcnt lgkmcnt(10)
	v_mfma_f32_16x16x32_bf16 v[132:135], v[150:153], v[186:189], v[132:135]
	v_mfma_f32_16x16x32_bf16 v[132:135], v[158:161], v[190:193], v[132:135]
	v_mfma_f32_16x16x32_bf16 v[128:131], v[166:169], v[190:193], v[128:131]
	v_mfma_f32_16x16x32_bf16 v[128:131], v[162:165], v[186:189], v[128:131]
	s_barrier
	s_setprio 1
	s_waitcnt lgkmcnt(0)
	v_mfma_f32_16x16x32_bf16 v[116:119], v[162:165], v[194:197], v[116:119]
	v_mfma_f32_16x16x32_bf16 v[116:119], v[166:169], v[198:201], v[116:119]
	v_mfma_f32_16x16x32_bf16 v[124:127], v[158:161], v[198:201], v[124:127]
	v_mfma_f32_16x16x32_bf16 v[124:127], v[150:153], v[194:197], v[124:127]
	v_mfma_f32_16x16x32_bf16 v[108:111], v[150:153], v[202:205], v[108:111]
	v_mfma_f32_16x16x32_bf16 v[108:111], v[158:161], v[206:209], v[108:111]
	v_mfma_f32_16x16x32_bf16 v[100:103], v[166:169], v[206:209], v[100:103]
	v_mfma_f32_16x16x32_bf16 v[100:103], v[162:165], v[202:205], v[100:103]
	v_mfma_f32_16x16x32_bf16 v[84:87], v[162:165], v[210:213], v[84:87]
	v_mfma_f32_16x16x32_bf16 v[84:87], v[166:169], v[214:217], v[84:87]
	v_mfma_f32_16x16x32_bf16 v[92:95], v[158:161], v[214:217], v[92:95]
	v_mfma_f32_16x16x32_bf16 v[92:95], v[150:153], v[210:213], v[92:95]
	s_setprio 0
	s_setprio 1
	v_mfma_f32_16x16x32_bf16 v[76:79], v[170:173], v[210:213], v[76:79]
	v_mfma_f32_16x16x32_bf16 v[76:79], v[174:177], v[214:217], v[76:79]
	v_mfma_f32_16x16x32_bf16 v[120:123], v[174:177], v[190:193], v[120:123]
	v_mfma_f32_16x16x32_bf16 v[120:123], v[170:173], v[186:189], v[120:123]
	v_mfma_f32_16x16x32_bf16 v[112:115], v[178:181], v[186:189], v[112:115]
	v_mfma_f32_16x16x32_bf16 v[112:115], v[182:185], v[190:193], v[112:115]
	v_mfma_f32_16x16x32_bf16 v[96:99], v[182:185], v[198:201], v[96:99]
	v_mfma_f32_16x16x32_bf16 v[96:99], v[178:181], v[194:197], v[96:99]
	v_mfma_f32_16x16x32_bf16 v[104:107], v[170:173], v[194:197], v[104:107]
	v_mfma_f32_16x16x32_bf16 v[104:107], v[174:177], v[198:201], v[104:107]
	v_mfma_f32_16x16x32_bf16 v[88:91], v[174:177], v[206:209], v[88:91]
	v_mfma_f32_16x16x32_bf16 v[88:91], v[170:173], v[202:205], v[88:91]
	v_mfma_f32_16x16x32_bf16 v[80:83], v[178:181], v[202:205], v[80:83]
	v_mfma_f32_16x16x32_bf16 v[80:83], v[182:185], v[206:209], v[80:83]
	v_mfma_f32_16x16x32_bf16 v[72:75], v[182:185], v[214:217], v[72:75]
	v_mfma_f32_16x16x32_bf16 v[72:75], v[178:181], v[210:213], v[72:75]
	s_setprio 0
	s_barrier
	s_add_i32 s68, s68, s29
	s_mov_b32 m0, s68
	ds_read_b128 v[186:189], v157 offset:16384
	ds_read_b128 v[190:193], v157 offset:17408
	ds_read_b128 v[194:197], v157 offset:18432
	ds_read_b128 v[198:201], v157 offset:19456
	ds_read_b128 v[202:205], v157 offset:20480
	ds_read_b128 v[206:209], v157 offset:21504
	ds_read_b128 v[210:213], v157 offset:22528
	ds_read_b128 v[214:217], v157 offset:23552
	global_load_lds_dwordx4 v140, s[24:25]
	s_add_i32 m0, s68, 0x2000
	s_add_u32 s68, s24, 0x4000
	s_addc_u32 s69, s25, 0
	s_add_i32 s77, s77, s29
	global_load_lds_dwordx4 v136, s[24:25]
	s_mov_b32 m0, s77
	s_nop 0
	global_load_lds_dwordx4 v140, s[68:69]
	s_add_i32 m0, s77, 0x2000
	s_nop 0
	global_load_lds_dwordx4 v136, s[68:69]
	s_mov_b32 m0, s31
	s_nop 0
	global_load_lds_dwordx4 v142, s[26:27]
	s_mov_b32 m0, s34
	s_nop 0
	global_load_lds_dwordx4 v138, s[26:27]
	s_waitcnt vmcnt(8)
	s_waitcnt lgkmcnt(6)
	v_mfma_f32_16x16x32_bf16 v[68:71], v[150:153], v[186:189], v[68:71]
	v_mfma_f32_16x16x32_bf16 v[68:71], v[158:161], v[190:193], v[68:71]
	v_mfma_f32_16x16x32_bf16 v[64:67], v[166:169], v[190:193], v[64:67]
	v_mfma_f32_16x16x32_bf16 v[64:67], v[162:165], v[186:189], v[64:67]
	s_barrier
; #define PG8_STAGE(bufoff, gbase, voff) do { _Pragma("unroll") for (int _i = 0; _i < 2; ++_i) \
;         __builtin_amdgcn_global_load_lds((const unsigned*)((const char*)(gbase) + (voff)[_i]), (PG8_LAS unsigned*)(lds + (bufoff) + ldsw + _i * 8192), 16, 0, 0); } while (0)
; #define PG8_LDA(dst, b, h) do { _Pragma("unroll") for (int m = 0; m < 4; ++m) _Pragma("unroll") for (int k = 0; k < 2; ++k) dst[m][k] = *(const PG8_LAS bf16x8*)(lds + PG8_SA(b, h) + aoff + m * 2048 + k * 1024); } while (0)
; #define PG8_LDB(dst, b, h) do { _Pragma("unroll") for (int n = 0; n < 2; ++n) _Pragma("unroll") for (int k = 0; k < 2; ++k) dst[n][k] = *(const PG8_LAS bf16x8*)(lds + PG8_SB(b, h) + boff + n * 2048 + k * 1024); } while (0)
; #define PG8_MMA(ai, bj, At, Bt) do { __builtin_amdgcn_s_setprio(1); _Pragma("unroll") for (int m = 0; m < 4; ++m) _Pragma("unroll") for (int n = 0; n < 2; ++n) _Pragma("unroll") for (int k = 0; k < 2; ++k) \
;         acc[ai][bj][m][n] = __builtin_amdgcn_mfma_f32_16x16x32_bf16(Bt[n][k], At[m][k], acc[ai][bj][m][n], 0, 0, 0); __builtin_amdgcn_s_setprio(0); } while (0)
; #define PG8_WAIT_V(n) asm volatile("s_waitcnt vmcnt(" #n ")" ::: "memory")
; #define PG8_WAIT_L(n) asm volatile("s_waitcnt lgkmcnt(" #n ")" ::: "memory")
; #define PG8_BAR __builtin_amdgcn_s_barrier()
; #define PG8_SCHED __builtin_amdgcn_sched_barrier(0)
; template <class Epi, class Sched, bool ALIGN_EPI = false, bool SP2 = false, bool ABLK = false, bool BBLK = false>
; __device__ __forceinline__ void gemm_phase(PG8_LAS unsigned char* lds, const Gemm g, const Sched& S, const Epi& E) {
;     ...
;             PG8_WAIT_V(8); PG8_WAIT_L(0); PG8_BAR; PG8_MMA(1, 0, At, B0); PG8_MMA(1, 1, At, B1); PG8_BAR; PG8_SCHED;
;             PG8_LDB(B0, 1, 0); PG8_LDB(B1, 1, 1); PG8_SCHED; PG8_LDA(At, 1, 0); PG8_STAGE(PG8_SA(0, 1), a2 + hstepA, voffA);
;             PG8_WAIT_V(8); PG8_WAIT_L(0); PG8_BAR; PG8_MMA(0, 0, At, B0); PG8_MMA(0, 1, At, B1); PG8_BAR; PG8_SCHED;
	s_setprio 1
	s_waitcnt lgkmcnt(0)
	v_mfma_f32_16x16x32_bf16 v[52:55], v[162:165], v[194:197], v[52:55]
	v_mfma_f32_16x16x32_bf16 v[52:55], v[166:169], v[198:201], v[52:55]
	v_mfma_f32_16x16x32_bf16 v[60:63], v[158:161], v[198:201], v[60:63]
	v_mfma_f32_16x16x32_bf16 v[60:63], v[150:153], v[194:197], v[60:63]
	v_mfma_f32_16x16x32_bf16 v[44:47], v[150:153], v[202:205], v[44:47]
	v_mfma_f32_16x16x32_bf16 v[44:47], v[158:161], v[206:209], v[44:47]
	v_mfma_f32_16x16x32_bf16 v[32:35], v[166:169], v[206:209], v[32:35]
	v_mfma_f32_16x16x32_bf16 v[32:35], v[162:165], v[202:205], v[32:35]
	v_mfma_f32_16x16x32_bf16 v[16:19], v[162:165], v[210:213], v[16:19]
	v_mfma_f32_16x16x32_bf16 v[16:19], v[166:169], v[214:217], v[16:19]
	v_mfma_f32_16x16x32_bf16 v[24:27], v[158:161], v[214:217], v[24:27]
	v_mfma_f32_16x16x32_bf16 v[24:27], v[150:153], v[210:213], v[24:27]
	s_setprio 0
	s_setprio 1
	v_mfma_f32_16x16x32_bf16 v[8:11], v[170:173], v[210:213], v[8:11]
	v_mfma_f32_16x16x32_bf16 v[8:11], v[174:177], v[214:217], v[8:11]
	v_mfma_f32_16x16x32_bf16 v[56:59], v[174:177], v[190:193], v[56:59]
	v_mfma_f32_16x16x32_bf16 v[56:59], v[170:173], v[186:189], v[56:59]
	v_mfma_f32_16x16x32_bf16 v[48:51], v[178:181], v[186:189], v[48:51]
	v_mfma_f32_16x16x32_bf16 v[48:51], v[182:185], v[190:193], v[48:51]
	v_mfma_f32_16x16x32_bf16 v[28:31], v[182:185], v[198:201], v[28:31]
	v_mfma_f32_16x16x32_bf16 v[28:31], v[178:181], v[194:197], v[28:31]
	v_mfma_f32_16x16x32_bf16 v[40:43], v[170:173], v[194:197], v[40:43]
	v_mfma_f32_16x16x32_bf16 v[40:43], v[174:177], v[198:201], v[40:43]
	v_mfma_f32_16x16x32_bf16 v[20:23], v[174:177], v[206:209], v[20:23]
	v_mfma_f32_16x16x32_bf16 v[20:23], v[170:173], v[202:205], v[20:23]
	v_mfma_f32_16x16x32_bf16 v[12:15], v[178:181], v[202:205], v[12:15]
	v_mfma_f32_16x16x32_bf16 v[12:15], v[182:185], v[206:209], v[12:15]
	v_mfma_f32_16x16x32_bf16 v[4:7], v[182:185], v[214:217], v[4:7]
	v_mfma_f32_16x16x32_bf16 v[4:7], v[178:181], v[210:213], v[4:7]
	s_setprio 0
	s_barrier
	s_add_i32 s68, 0, 0x18000
	v_add_u32_e32 v36, s68, v155
	s_add_i32 s69, 0, 0x1c000
	ds_read_b128 v[150:153], v36
	ds_read_b128 v[158:161], v36 offset:1024
	ds_read_b128 v[162:165], v36 offset:2048
	ds_read_b128 v[166:169], v36 offset:3072
	ds_read_b128 v[186:189], v157 offset:32768
	ds_read_b128 v[190:193], v157 offset:33792
	v_add_u32_e32 v36, s69, v155
	ds_read_b128 v[170:173], v36
	ds_read_b128 v[174:177], v36 offset:1024
	ds_read_b128 v[178:181], v36 offset:2048
	ds_read_b128 v[182:185], v36 offset:3072
	s_add_u32 s26, s26, 0x4000
	s_addc_u32 s27, s27, 0
	s_mov_b32 m0, s35
	ds_read_b128 v[194:197], v157 offset:34816
	ds_read_b128 v[198:201], v157 offset:35840
	ds_read_b128 v[202:205], v157 offset:36864
	ds_read_b128 v[206:209], v157 offset:37888
	ds_read_b128 v[210:213], v157 offset:38912
	ds_read_b128 v[214:217], v157 offset:39936
	global_load_lds_dwordx4 v142, s[26:27]
	s_mov_b32 m0, s36
	s_nop 0
	global_load_lds_dwordx4 v138, s[26:27]
	s_waitcnt vmcnt(8)
	s_waitcnt lgkmcnt(10)
	v_mfma_f32_16x16x32_bf16 v[132:135], v[150:153], v[186:189], v[132:135]
	v_mfma_f32_16x16x32_bf16 v[132:135], v[158:161], v[190:193], v[132:135]
	v_mfma_f32_16x16x32_bf16 v[128:131], v[166:169], v[190:193], v[128:131]
	v_mfma_f32_16x16x32_bf16 v[128:131], v[162:165], v[186:189], v[128:131]
	s_barrier
	s_setprio 1
	s_waitcnt lgkmcnt(0)
	v_mfma_f32_16x16x32_bf16 v[116:119], v[162:165], v[194:197], v[116:119]
	v_mfma_f32_16x16x32_bf16 v[116:119], v[166:169], v[198:201], v[116:119]
	v_mfma_f32_16x16x32_bf16 v[124:127], v[158:161], v[198:201], v[124:127]
	v_mfma_f32_16x16x32_bf16 v[124:127], v[150:153], v[194:197], v[124:127]
	v_mfma_f32_16x16x32_bf16 v[108:111], v[150:153], v[202:205], v[108:111]
	v_mfma_f32_16x16x32_bf16 v[108:111], v[158:161], v[206:209], v[108:111]
	v_mfma_f32_16x16x32_bf16 v[100:103], v[166:169], v[206:209], v[100:103]
	v_mfma_f32_16x16x32_bf16 v[100:103], v[162:165], v[202:205], v[100:103]
	v_mfma_f32_16x16x32_bf16 v[84:87], v[162:165], v[210:213], v[84:87]
	v_mfma_f32_16x16x32_bf16 v[84:87], v[166:169], v[214:217], v[84:87]
	v_mfma_f32_16x16x32_bf16 v[92:95], v[158:161], v[214:217], v[92:95]
	v_mfma_f32_16x16x32_bf16 v[92:95], v[150:153], v[210:213], v[92:95]
	s_setprio 0
	s_setprio 1
	v_mfma_f32_16x16x32_bf16 v[76:79], v[170:173], v[210:213], v[76:79]
	v_mfma_f32_16x16x32_bf16 v[76:79], v[174:177], v[214:217], v[76:79]
	v_mfma_f32_16x16x32_bf16 v[120:123], v[174:177], v[190:193], v[120:123]
	v_mfma_f32_16x16x32_bf16 v[120:123], v[170:173], v[186:189], v[120:123]
	v_mfma_f32_16x16x32_bf16 v[112:115], v[178:181], v[186:189], v[112:115]
	v_mfma_f32_16x16x32_bf16 v[112:115], v[182:185], v[190:193], v[112:115]
	v_mfma_f32_16x16x32_bf16 v[96:99], v[182:185], v[198:201], v[96:99]
	v_mfma_f32_16x16x32_bf16 v[96:99], v[178:181], v[194:197], v[96:99]
	v_mfma_f32_16x16x32_bf16 v[104:107], v[170:173], v[194:197], v[104:107]
	v_mfma_f32_16x16x32_bf16 v[104:107], v[174:177], v[198:201], v[104:107]
	v_mfma_f32_16x16x32_bf16 v[88:91], v[174:177], v[206:209], v[88:91]
	v_mfma_f32_16x16x32_bf16 v[88:91], v[170:173], v[202:205], v[88:91]
	v_mfma_f32_16x16x32_bf16 v[80:83], v[178:181], v[202:205], v[80:83]
	v_mfma_f32_16x16x32_bf16 v[80:83], v[182:185], v[206:209], v[80:83]
	v_mfma_f32_16x16x32_bf16 v[72:75], v[182:185], v[214:217], v[72:75]
	v_mfma_f32_16x16x32_bf16 v[72:75], v[178:181], v[210:213], v[72:75]
	s_setprio 0
	s_barrier
; #define PG8_STAGE(bufoff, gbase, voff) do { _Pragma("unroll") for (int _i = 0; _i < 2; ++_i) \
;         __builtin_amdgcn_global_load_lds((const unsigned*)((const char*)(gbase) + (voff)[_i]), (PG8_LAS unsigned*)(lds + (bufoff) + ldsw + _i * 8192), 16, 0, 0); } while (0)
; #define PG8_LDA(dst, b, h) do { _Pragma("unroll") for (int m = 0; m < 4; ++m) _Pragma("unroll") for (int k = 0; k < 2; ++k) dst[m][k] = *(const PG8_LAS bf16x8*)(lds + PG8_SA(b, h) + aoff + m * 2048 + k * 1024); } while (0)
; #define PG8_MMA(ai, bj, At, Bt) do { __builtin_amdgcn_s_setprio(1); _Pragma("unroll") for (int m = 0; m < 4; ++m) _Pragma("unroll") for (int n = 0; n < 2; ++n) _Pragma("unroll") for (int k = 0; k < 2; ++k) \
;         acc[ai][bj][m][n] = __builtin_amdgcn_mfma_f32_16x16x32_bf16(Bt[n][k], At[m][k], acc[ai][bj][m][n], 0, 0, 0); __builtin_amdgcn_s_setprio(0); } while (0)
; #define PG8_WAIT_V(n) asm volatile("s_waitcnt vmcnt(" #n ")" ::: "memory")
; #define PG8_WAIT_L(n) asm volatile("s_waitcnt lgkmcnt(" #n ")" ::: "memory")
; #define PG8_BAR __builtin_amdgcn_s_barrier()
; #define PG8_SCHED __builtin_amdgcn_sched_barrier(0)
; template <class Epi, class Sched, bool ALIGN_EPI = false, bool SP2 = false, bool ABLK = false, bool BBLK = false>
; __device__ __forceinline__ void gemm_phase(PG8_LAS unsigned char* lds, const Gemm g, const Sched& S, const Epi& E) {
;     ...
;             PG8_LDA(At, 1, 1); PG8_STAGE(PG8_SB(1, 0), b3, voffB); PG8_STAGE(PG8_SB(1, 1), b3 + hstepB, voffB); PG8_STAGE(PG8_SA(1, 0), a3, voffA);
;             PG8_WAIT_V(8); PG8_WAIT_L(0); PG8_BAR; PG8_MMA(1, 0, At, B0); PG8_MMA(1, 1, At, B1); PG8_BAR; PG8_SCHED;
	s_add_u32 s26, s24, 0x8000
	s_addc_u32 s27, s25, 0
	s_add_i32 s68, s68, s29
	s_mov_b32 m0, s68
	ds_read_b128 v[186:189], v157 offset:49152
	ds_read_b128 v[190:193], v157 offset:50176
	ds_read_b128 v[194:197], v157 offset:51200
	ds_read_b128 v[198:201], v157 offset:52224
	ds_read_b128 v[202:205], v157 offset:53248
	ds_read_b128 v[206:209], v157 offset:54272
	ds_read_b128 v[210:213], v157 offset:55296
	ds_read_b128 v[214:217], v157 offset:56320
	global_load_lds_dwordx4 v140, s[26:27]
	s_add_i32 m0, s68, 0x2000
	s_add_u32 s24, s24, 0xc000
	s_addc_u32 s25, s25, 0
	global_load_lds_dwordx4 v136, s[26:27]
	s_add_i32 s26, s69, s29
	s_mov_b32 m0, s26
	s_nop 0
	global_load_lds_dwordx4 v140, s[24:25]
	s_add_i32 m0, s26, 0x2000
	s_nop 0
	global_load_lds_dwordx4 v136, s[24:25]
	s_mov_b32 m0, s37
	s_nop 0
	global_load_lds_dwordx4 v142, s[22:23]
	s_mov_b32 m0, s62
	s_nop 0
	global_load_lds_dwordx4 v138, s[22:23]
	s_waitcnt vmcnt(8)
	s_waitcnt lgkmcnt(6)
	v_mfma_f32_16x16x32_bf16 v[68:71], v[150:153], v[186:189], v[68:71]
	v_mfma_f32_16x16x32_bf16 v[68:71], v[158:161], v[190:193], v[68:71]
	v_mfma_f32_16x16x32_bf16 v[64:67], v[166:169], v[190:193], v[64:67]
	v_mfma_f32_16x16x32_bf16 v[64:67], v[162:165], v[186:189], v[64:67]
	s_barrier
	s_setprio 1
	s_waitcnt lgkmcnt(0)
	v_mfma_f32_16x16x32_bf16 v[52:55], v[162:165], v[194:197], v[52:55]
	v_mfma_f32_16x16x32_bf16 v[52:55], v[166:169], v[198:201], v[52:55]
	v_mfma_f32_16x16x32_bf16 v[60:63], v[158:161], v[198:201], v[60:63]
	v_mfma_f32_16x16x32_bf16 v[60:63], v[150:153], v[194:197], v[60:63]
	v_mfma_f32_16x16x32_bf16 v[44:47], v[150:153], v[202:205], v[44:47]
	v_mfma_f32_16x16x32_bf16 v[44:47], v[158:161], v[206:209], v[44:47]
	v_mfma_f32_16x16x32_bf16 v[32:35], v[166:169], v[206:209], v[32:35]
	v_mfma_f32_16x16x32_bf16 v[32:35], v[162:165], v[202:205], v[32:35]
	v_mfma_f32_16x16x32_bf16 v[16:19], v[162:165], v[210:213], v[16:19]
	v_mfma_f32_16x16x32_bf16 v[16:19], v[166:169], v[214:217], v[16:19]
	v_mfma_f32_16x16x32_bf16 v[24:27], v[158:161], v[214:217], v[24:27]
	v_mfma_f32_16x16x32_bf16 v[24:27], v[150:153], v[210:213], v[24:27]
	s_setprio 0
	s_setprio 1
	v_mfma_f32_16x16x32_bf16 v[8:11], v[170:173], v[210:213], v[8:11]
	v_mfma_f32_16x16x32_bf16 v[8:11], v[174:177], v[214:217], v[8:11]
	v_mfma_f32_16x16x32_bf16 v[56:59], v[174:177], v[190:193], v[56:59]
	v_mfma_f32_16x16x32_bf16 v[56:59], v[170:173], v[186:189], v[56:59]
	v_mfma_f32_16x16x32_bf16 v[48:51], v[178:181], v[186:189], v[48:51]
	v_mfma_f32_16x16x32_bf16 v[48:51], v[182:185], v[190:193], v[48:51]
	v_mfma_f32_16x16x32_bf16 v[28:31], v[182:185], v[198:201], v[28:31]
	v_mfma_f32_16x16x32_bf16 v[28:31], v[178:181], v[194:197], v[28:31]
	v_mfma_f32_16x16x32_bf16 v[40:43], v[170:173], v[194:197], v[40:43]
	v_mfma_f32_16x16x32_bf16 v[40:43], v[174:177], v[198:201], v[40:43]
	v_mfma_f32_16x16x32_bf16 v[20:23], v[174:177], v[206:209], v[20:23]
	v_mfma_f32_16x16x32_bf16 v[20:23], v[170:173], v[202:205], v[20:23]
	v_mfma_f32_16x16x32_bf16 v[12:15], v[178:181], v[202:205], v[12:15]
	v_mfma_f32_16x16x32_bf16 v[12:15], v[182:185], v[206:209], v[12:15]
	v_mfma_f32_16x16x32_bf16 v[4:7], v[182:185], v[214:217], v[4:7]
	v_mfma_f32_16x16x32_bf16 v[4:7], v[178:181], v[210:213], v[4:7]
	s_setprio 0
	s_barrier
	s_add_i32 s13, s13, 2
	s_add_u32 s20, s20, 0x10000
	s_addc_u32 s21, s21, 0
	s_add_u32 s70, s70, 0x10000
	s_addc_u32 s71, s71, 0
	s_cmp_gt_u32 s13, 29
	s_cbranch_scc0 .LBB0_916
	s_and_b64 vcc, exec, s[6:7]
	s_cbranch_vccz .LBB0_919
	s_barrier

; #define PG8_STAGE(bufoff, gbase, voff) do { _Pragma("unroll") for (int _i = 0; _i < 2; ++_i) \
;         __builtin_amdgcn_global_load_lds((const unsigned*)((const char*)(gbase) + (voff)[_i]), (PG8_LAS unsigned*)(lds + (bufoff) + ldsw + _i * 8192), 16, 0, 0); } while (0)
; #define PG8_LDA(dst, b, h) do { _Pragma("unroll") for (int m = 0; m < 4; ++m) _Pragma("unroll") for (int k = 0; k < 2; ++k) dst[m][k] = *(const PG8_LAS bf16x8*)(lds + PG8_SA(b, h) + aoff + m * 2048 + k * 1024); } while (0)
; #define PG8_LDB(dst, b, h) do { _Pragma("unroll") for (int n = 0; n < 2; ++n) _Pragma("unroll") for (int k = 0; k < 2; ++k) dst[n][k] = *(const PG8_LAS bf16x8*)(lds + PG8_SB(b, h) + boff + n * 2048 + k * 1024); } while (0)
; #define PG8_MMA(ai, bj, At, Bt) do { __builtin_amdgcn_s_setprio(1); _Pragma("unroll") for (int m = 0; m < 4; ++m) _Pragma("unroll") for (int n = 0; n < 2; ++n) _Pragma("unroll") for (int k = 0; k < 2; ++k) \
;         acc[ai][bj][m][n] = __builtin_amdgcn_mfma_f32_16x16x32_bf16(Bt[n][k], At[m][k], acc[ai][bj][m][n], 0, 0, 0); __builtin_amdgcn_s_setprio(0); } while (0)
; #define PG8_WAIT_V(n) asm volatile("s_waitcnt vmcnt(" #n ")" ::: "memory")
; #define PG8_BAR __builtin_amdgcn_s_barrier()
; template <class Epi, class Sched, bool ALIGN_EPI = false, bool SP2 = false, bool ABLK = false, bool BBLK = false>
; __device__ __forceinline__ void gemm_phase(PG8_LAS unsigned char* lds, const Gemm g, const Sched& S, const Epi& E) {
;     ...
;             const bool last = (t == nt - 2);
;             const char* a1 = cA + (size_t)(t + 1) * kstepA;
;             const char* a2 = last ? nA : cA + (size_t)(t + 2) * kstepA; const char* b2 = last ? nB : cB + (size_t)(t + 2) * kstepB;
;             const char* a3 = a2 + kstepA; const char* b3 = b2 + kstepB;
;             if (last && has_next) S.a_ready(nxt);
;             if constexpr (SP2) {
;             PG8_LDB(B0, 0, 0); PG8_LDB(B1, 0, 1); PG8_SCHED; PG8_LDA(At, 0, 0); PG8_STAGE(PG8_SA(1, 1), a1 + hstepA, voffA);
;             PG8_WAIT_V(8); PG8_WAIT_L(0); PG8_BAR; PG8_MMA(0, 0, At, B0); PG8_MMA(0, 1, At, B1); PG8_BAR; PG8_SCHED;
;             PG8_LDA(At, 0, 1); PG8_STAGE(PG8_SB(0, 0), b2, voffB); PG8_STAGE(PG8_SB(0, 1), b2 + hstepB, voffB); PG8_STAGE(PG8_SA(0, 0), a2, voffA);
;             PG8_WAIT_V(8); PG8_WAIT_L(0); PG8_BAR; PG8_MMA(1, 0, At, B0); PG8_MMA(1, 1, At, B1); PG8_BAR; PG8_SCHED;
.LBB0_2111:
	s_add_u32 s24, s22, 0x4000
	s_addc_u32 s25, s23, 0
	s_cmp_eq_u32 s13, 28
	s_cselect_b32 s28, s17, s24
	s_cselect_b32 s29, s12, s25
	s_cselect_b32 s26, s77, s82
	s_cselect_b32 s27, s11, vcc_lo
	s_add_u32 s24, s28, 0x8000
	s_addc_u32 s25, s29, 0
	s_add_i32 s68, 0, 0x10000
	v_add_u32_e32 v151, s68, v148
	s_add_i32 s88, 0, 0x14000
	ds_read_b128 v[36:39], v151
	ds_read_b128 v[152:155], v151 offset:1024
	ds_read_b128 v[156:159], v151 offset:2048
	ds_read_b128 v[160:163], v151 offset:3072
	ds_read_b128 v[180:183], v150
	ds_read_b128 v[184:187], v150 offset:1024
	v_add_u32_e32 v151, s88, v148
	ds_read_b128 v[164:167], v151
	ds_read_b128 v[168:171], v151 offset:1024
	ds_read_b128 v[172:175], v151 offset:2048
	ds_read_b128 v[176:179], v151 offset:3072
	s_add_i32 m0, s9, 0xc000
	ds_read_b128 v[188:191], v150 offset:2048
	ds_read_b128 v[192:195], v150 offset:3072
	ds_read_b128 v[196:199], v150 offset:4096
	ds_read_b128 v[200:203], v150 offset:5120
	ds_read_b128 v[204:207], v150 offset:6144
	ds_read_b128 v[208:211], v150 offset:7168
	global_load_lds_dwordx4 v144, s[22:23]
	s_add_i32 m0, s9, 0xe000
	s_nop 0
	global_load_lds_dwordx4 v146, s[22:23]
	s_waitcnt vmcnt(8)
	s_waitcnt lgkmcnt(10)
	v_mfma_f32_16x16x32_bf16 v[132:135], v[36:39], v[180:183], v[132:135]
	v_mfma_f32_16x16x32_bf16 v[132:135], v[152:155], v[184:187], v[132:135]
	v_mfma_f32_16x16x32_bf16 v[128:131], v[160:163], v[184:187], v[128:131]
	v_mfma_f32_16x16x32_bf16 v[128:131], v[156:159], v[180:183], v[128:131]
	s_barrier
	s_setprio 1
	s_waitcnt lgkmcnt(0)
	v_mfma_f32_16x16x32_bf16 v[120:123], v[156:159], v[188:191], v[120:123]
	v_mfma_f32_16x16x32_bf16 v[120:123], v[160:163], v[192:195], v[120:123]
	v_mfma_f32_16x16x32_bf16 v[124:127], v[152:155], v[192:195], v[124:127]
	v_mfma_f32_16x16x32_bf16 v[124:127], v[36:39], v[188:191], v[124:127]
	v_mfma_f32_16x16x32_bf16 v[108:111], v[36:39], v[196:199], v[108:111]
	v_mfma_f32_16x16x32_bf16 v[108:111], v[152:155], v[200:203], v[108:111]
	v_mfma_f32_16x16x32_bf16 v[104:107], v[160:163], v[200:203], v[104:107]
	v_mfma_f32_16x16x32_bf16 v[104:107], v[156:159], v[196:199], v[104:107]
	v_mfma_f32_16x16x32_bf16 v[88:91], v[156:159], v[204:207], v[88:91]
	v_mfma_f32_16x16x32_bf16 v[88:91], v[160:163], v[208:211], v[88:91]
	v_mfma_f32_16x16x32_bf16 v[92:95], v[152:155], v[208:211], v[92:95]
	v_mfma_f32_16x16x32_bf16 v[92:95], v[36:39], v[204:207], v[92:95]
	s_setprio 0
	s_setprio 1
	v_mfma_f32_16x16x32_bf16 v[76:79], v[164:167], v[204:207], v[76:79]
	v_mfma_f32_16x16x32_bf16 v[76:79], v[168:171], v[208:211], v[76:79]
	v_mfma_f32_16x16x32_bf16 v[116:119], v[168:171], v[184:187], v[116:119]
	v_mfma_f32_16x16x32_bf16 v[116:119], v[164:167], v[180:183], v[116:119]
	v_mfma_f32_16x16x32_bf16 v[112:115], v[172:175], v[180:183], v[112:115]
	v_mfma_f32_16x16x32_bf16 v[112:115], v[176:179], v[184:187], v[112:115]
	v_mfma_f32_16x16x32_bf16 v[96:99], v[176:179], v[192:195], v[96:99]
	v_mfma_f32_16x16x32_bf16 v[96:99], v[172:175], v[188:191], v[96:99]
	v_mfma_f32_16x16x32_bf16 v[100:103], v[164:167], v[188:191], v[100:103]
	v_mfma_f32_16x16x32_bf16 v[100:103], v[168:171], v[192:195], v[100:103]
	v_mfma_f32_16x16x32_bf16 v[84:87], v[168:171], v[200:203], v[84:87]
	v_mfma_f32_16x16x32_bf16 v[84:87], v[164:167], v[196:199], v[84:87]
	v_mfma_f32_16x16x32_bf16 v[80:83], v[172:175], v[196:199], v[80:83]
	v_mfma_f32_16x16x32_bf16 v[80:83], v[176:179], v[200:203], v[80:83]
	v_mfma_f32_16x16x32_bf16 v[72:75], v[176:179], v[208:211], v[72:75]
	v_mfma_f32_16x16x32_bf16 v[72:75], v[172:175], v[204:207], v[72:75]
	s_setprio 0
	s_barrier
	s_add_i32 s68, s68, s34
	s_mov_b32 m0, s68
	ds_read_b128 v[180:183], v150 offset:16384
	ds_read_b128 v[184:187], v150 offset:17408
	ds_read_b128 v[188:191], v150 offset:18432
	ds_read_b128 v[192:195], v150 offset:19456
	ds_read_b128 v[196:199], v150 offset:20480
	ds_read_b128 v[200:203], v150 offset:21504
	ds_read_b128 v[204:207], v150 offset:22528
	ds_read_b128 v[208:211], v150 offset:23552
	global_load_lds_dwordx4 v138, s[26:27]
	s_add_i32 m0, s68, 0x2000
	s_add_u32 s68, s26, 0x4000
	s_addc_u32 s69, s27, 0
	s_add_i32 s88, s88, s34
	global_load_lds_dwordx4 v142, s[26:27]
	s_mov_b32 m0, s88
	s_nop 0
	global_load_lds_dwordx4 v138, s[68:69]
	s_add_i32 m0, s88, 0x2000
	s_nop 0
	global_load_lds_dwordx4 v142, s[68:69]
	s_mov_b32 m0, s9
	s_nop 0
	global_load_lds_dwordx4 v136, s[28:29]
	s_mov_b32 m0, s35
	s_nop 0
	global_load_lds_dwordx4 v140, s[28:29]
	s_waitcnt vmcnt(8)
	s_waitcnt lgkmcnt(6)
	v_mfma_f32_16x16x32_bf16 v[68:71], v[36:39], v[180:183], v[68:71]
	v_mfma_f32_16x16x32_bf16 v[68:71], v[152:155], v[184:187], v[68:71]
	v_mfma_f32_16x16x32_bf16 v[64:67], v[160:163], v[184:187], v[64:67]
	v_mfma_f32_16x16x32_bf16 v[64:67], v[156:159], v[180:183], v[64:67]
	s_barrier
; #define PG8_STAGE(bufoff, gbase, voff) do { _Pragma("unroll") for (int _i = 0; _i < 2; ++_i) \
;         __builtin_amdgcn_global_load_lds((const unsigned*)((const char*)(gbase) + (voff)[_i]), (PG8_LAS unsigned*)(lds + (bufoff) + ldsw + _i * 8192), 16, 0, 0); } while (0)
; #define PG8_LDA(dst, b, h) do { _Pragma("unroll") for (int m = 0; m < 4; ++m) _Pragma("unroll") for (int k = 0; k < 2; ++k) dst[m][k] = *(const PG8_LAS bf16x8*)(lds + PG8_SA(b, h) + aoff + m * 2048 + k * 1024); } while (0)
; #define PG8_LDB(dst, b, h) do { _Pragma("unroll") for (int n = 0; n < 2; ++n) _Pragma("unroll") for (int k = 0; k < 2; ++k) dst[n][k] = *(const PG8_LAS bf16x8*)(lds + PG8_SB(b, h) + boff + n * 2048 + k * 1024); } while (0)
; #define PG8_MMA(ai, bj, At, Bt) do { __builtin_amdgcn_s_setprio(1); _Pragma("unroll") for (int m = 0; m < 4; ++m) _Pragma("unroll") for (int n = 0; n < 2; ++n) _Pragma("unroll") for (int k = 0; k < 2; ++k) \
;         acc[ai][bj][m][n] = __builtin_amdgcn_mfma_f32_16x16x32_bf16(Bt[n][k], At[m][k], acc[ai][bj][m][n], 0, 0, 0); __builtin_amdgcn_s_setprio(0); } while (0)
; #define PG8_WAIT_V(n) asm volatile("s_waitcnt vmcnt(" #n ")" ::: "memory")
; #define PG8_WAIT_L(n) asm volatile("s_waitcnt lgkmcnt(" #n ")" ::: "memory")
; #define PG8_BAR __builtin_amdgcn_s_barrier()
; #define PG8_SCHED __builtin_amdgcn_sched_barrier(0)
; template <class Epi, class Sched, bool ALIGN_EPI = false, bool SP2 = false, bool ABLK = false, bool BBLK = false>
; __device__ __forceinline__ void gemm_phase(PG8_LAS unsigned char* lds, const Gemm g, const Sched& S, const Epi& E) {
;     ...
;             PG8_WAIT_V(8); PG8_WAIT_L(0); PG8_BAR; PG8_MMA(1, 0, At, B0); PG8_MMA(1, 1, At, B1); PG8_BAR; PG8_SCHED;
;             PG8_LDB(B0, 1, 0); PG8_LDB(B1, 1, 1); PG8_SCHED; PG8_LDA(At, 1, 0); PG8_STAGE(PG8_SA(0, 1), a2 + hstepA, voffA);
;             PG8_WAIT_V(8); PG8_WAIT_L(0); PG8_BAR; PG8_MMA(0, 0, At, B0); PG8_MMA(0, 1, At, B1); PG8_BAR; PG8_SCHED;
	s_setprio 1
	s_waitcnt lgkmcnt(0)
	v_mfma_f32_16x16x32_bf16 v[56:59], v[156:159], v[188:191], v[56:59]
	v_mfma_f32_16x16x32_bf16 v[56:59], v[160:163], v[192:195], v[56:59]
	v_mfma_f32_16x16x32_bf16 v[60:63], v[152:155], v[192:195], v[60:63]
	v_mfma_f32_16x16x32_bf16 v[60:63], v[36:39], v[188:191], v[60:63]
	v_mfma_f32_16x16x32_bf16 v[44:47], v[36:39], v[196:199], v[44:47]
	v_mfma_f32_16x16x32_bf16 v[44:47], v[152:155], v[200:203], v[44:47]
	v_mfma_f32_16x16x32_bf16 v[40:43], v[160:163], v[200:203], v[40:43]
	v_mfma_f32_16x16x32_bf16 v[40:43], v[156:159], v[196:199], v[40:43]
	v_mfma_f32_16x16x32_bf16 v[20:23], v[156:159], v[204:207], v[20:23]
	v_mfma_f32_16x16x32_bf16 v[20:23], v[160:163], v[208:211], v[20:23]
	v_mfma_f32_16x16x32_bf16 v[24:27], v[152:155], v[208:211], v[24:27]
	v_mfma_f32_16x16x32_bf16 v[24:27], v[36:39], v[204:207], v[24:27]
	s_setprio 0
	s_setprio 1
	v_mfma_f32_16x16x32_bf16 v[48:51], v[172:175], v[180:183], v[48:51]
	v_mfma_f32_16x16x32_bf16 v[32:35], v[164:167], v[188:191], v[32:35]
	v_mfma_f32_16x16x32_bf16 v[28:31], v[172:175], v[188:191], v[28:31]
	v_mfma_f32_16x16x32_bf16 v[16:19], v[164:167], v[196:199], v[16:19]
	v_mfma_f32_16x16x32_bf16 v[12:15], v[172:175], v[196:199], v[12:15]
	v_mfma_f32_16x16x32_bf16 v[8:11], v[164:167], v[204:207], v[8:11]
	v_mfma_f32_16x16x32_bf16 v[4:7], v[172:175], v[204:207], v[4:7]
	v_mfma_f32_16x16x32_bf16 v[36:39], v[164:167], v[180:183], v[52:55]
	v_mfma_f32_16x16x32_bf16 v[48:51], v[176:179], v[184:187], v[48:51]
	v_mfma_f32_16x16x32_bf16 v[32:35], v[168:171], v[192:195], v[32:35]
	v_mfma_f32_16x16x32_bf16 v[28:31], v[176:179], v[192:195], v[28:31]
	v_mfma_f32_16x16x32_bf16 v[16:19], v[168:171], v[200:203], v[16:19]
	v_mfma_f32_16x16x32_bf16 v[12:15], v[176:179], v[200:203], v[12:15]
	v_mfma_f32_16x16x32_bf16 v[8:11], v[168:171], v[208:211], v[8:11]
	v_mfma_f32_16x16x32_bf16 v[4:7], v[176:179], v[208:211], v[4:7]
	v_mfma_f32_16x16x32_bf16 v[36:39], v[168:171], v[184:187], v[36:39]
	s_setprio 0
	s_barrier
	s_add_i32 s68, 0, 0x18000
	v_add_u32_e32 v151, s68, v148
	s_add_i32 s69, 0, 0x1c000
	ds_read_b128 v[52:55], v151
	ds_read_b128 v[152:155], v151 offset:1024
	ds_read_b128 v[156:159], v151 offset:2048
	ds_read_b128 v[160:163], v151 offset:3072
	ds_read_b128 v[180:183], v150 offset:32768
	ds_read_b128 v[184:187], v150 offset:33792
	v_add_u32_e32 v151, s69, v148
	ds_read_b128 v[164:167], v151
	ds_read_b128 v[168:171], v151 offset:1024
	ds_read_b128 v[172:175], v151 offset:2048
	ds_read_b128 v[176:179], v151 offset:3072
	s_add_u32 s28, s28, 0x4000
	s_addc_u32 s29, s29, 0
	s_mov_b32 m0, s36
	ds_read_b128 v[188:191], v150 offset:34816
	ds_read_b128 v[192:195], v150 offset:35840
	ds_read_b128 v[196:199], v150 offset:36864
	ds_read_b128 v[200:203], v150 offset:37888
	ds_read_b128 v[204:207], v150 offset:38912
	ds_read_b128 v[208:211], v150 offset:39936
	global_load_lds_dwordx4 v136, s[28:29]
	s_mov_b32 m0, s37
	s_nop 0
	global_load_lds_dwordx4 v140, s[28:29]
	s_waitcnt vmcnt(8)
	s_waitcnt lgkmcnt(10)
	v_mfma_f32_16x16x32_bf16 v[132:135], v[52:55], v[180:183], v[132:135]
	v_mfma_f32_16x16x32_bf16 v[132:135], v[152:155], v[184:187], v[132:135]
	v_mfma_f32_16x16x32_bf16 v[128:131], v[160:163], v[184:187], v[128:131]
	v_mfma_f32_16x16x32_bf16 v[128:131], v[156:159], v[180:183], v[128:131]
	s_barrier
	s_setprio 1
	s_waitcnt lgkmcnt(0)
	v_mfma_f32_16x16x32_bf16 v[120:123], v[156:159], v[188:191], v[120:123]
	v_mfma_f32_16x16x32_bf16 v[120:123], v[160:163], v[192:195], v[120:123]
	v_mfma_f32_16x16x32_bf16 v[124:127], v[152:155], v[192:195], v[124:127]
	v_mfma_f32_16x16x32_bf16 v[124:127], v[52:55], v[188:191], v[124:127]
	v_mfma_f32_16x16x32_bf16 v[108:111], v[52:55], v[196:199], v[108:111]
	v_mfma_f32_16x16x32_bf16 v[108:111], v[152:155], v[200:203], v[108:111]
	v_mfma_f32_16x16x32_bf16 v[104:107], v[160:163], v[200:203], v[104:107]
	v_mfma_f32_16x16x32_bf16 v[104:107], v[156:159], v[196:199], v[104:107]
	v_mfma_f32_16x16x32_bf16 v[88:91], v[156:159], v[204:207], v[88:91]
	v_mfma_f32_16x16x32_bf16 v[88:91], v[160:163], v[208:211], v[88:91]
	v_mfma_f32_16x16x32_bf16 v[92:95], v[152:155], v[208:211], v[92:95]
	v_mfma_f32_16x16x32_bf16 v[92:95], v[52:55], v[204:207], v[92:95]
	s_setprio 0
	s_setprio 1
	v_mfma_f32_16x16x32_bf16 v[76:79], v[164:167], v[204:207], v[76:79]
	v_mfma_f32_16x16x32_bf16 v[76:79], v[168:171], v[208:211], v[76:79]
	v_mfma_f32_16x16x32_bf16 v[116:119], v[168:171], v[184:187], v[116:119]
	v_mfma_f32_16x16x32_bf16 v[116:119], v[164:167], v[180:183], v[116:119]
	v_mfma_f32_16x16x32_bf16 v[112:115], v[172:175], v[180:183], v[112:115]
	v_mfma_f32_16x16x32_bf16 v[112:115], v[176:179], v[184:187], v[112:115]
	v_mfma_f32_16x16x32_bf16 v[96:99], v[176:179], v[192:195], v[96:99]
	v_mfma_f32_16x16x32_bf16 v[96:99], v[172:175], v[188:191], v[96:99]
	v_mfma_f32_16x16x32_bf16 v[100:103], v[164:167], v[188:191], v[100:103]
	v_mfma_f32_16x16x32_bf16 v[100:103], v[168:171], v[192:195], v[100:103]
	v_mfma_f32_16x16x32_bf16 v[84:87], v[168:171], v[200:203], v[84:87]
	v_mfma_f32_16x16x32_bf16 v[84:87], v[164:167], v[196:199], v[84:87]
	v_mfma_f32_16x16x32_bf16 v[80:83], v[172:175], v[196:199], v[80:83]
	v_mfma_f32_16x16x32_bf16 v[80:83], v[176:179], v[200:203], v[80:83]
	v_mfma_f32_16x16x32_bf16 v[72:75], v[176:179], v[208:211], v[72:75]
	v_mfma_f32_16x16x32_bf16 v[72:75], v[172:175], v[204:207], v[72:75]
	s_setprio 0
	s_barrier
; #define PG8_STAGE(bufoff, gbase, voff) do { _Pragma("unroll") for (int _i = 0; _i < 2; ++_i) \
;         __builtin_amdgcn_global_load_lds((const unsigned*)((const char*)(gbase) + (voff)[_i]), (PG8_LAS unsigned*)(lds + (bufoff) + ldsw + _i * 8192), 16, 0, 0); } while (0)
; #define PG8_LDA(dst, b, h) do { _Pragma("unroll") for (int m = 0; m < 4; ++m) _Pragma("unroll") for (int k = 0; k < 2; ++k) dst[m][k] = *(const PG8_LAS bf16x8*)(lds + PG8_SA(b, h) + aoff + m * 2048 + k * 1024); } while (0)
; #define PG8_MMA(ai, bj, At, Bt) do { __builtin_amdgcn_s_setprio(1); _Pragma("unroll") for (int m = 0; m < 4; ++m) _Pragma("unroll") for (int n = 0; n < 2; ++n) _Pragma("unroll") for (int k = 0; k < 2; ++k) \
;         acc[ai][bj][m][n] = __builtin_amdgcn_mfma_f32_16x16x32_bf16(Bt[n][k], At[m][k], acc[ai][bj][m][n], 0, 0, 0); __builtin_amdgcn_s_setprio(0); } while (0)
; #define PG8_WAIT_V(n) asm volatile("s_waitcnt vmcnt(" #n ")" ::: "memory")
; #define PG8_WAIT_L(n) asm volatile("s_waitcnt lgkmcnt(" #n ")" ::: "memory")
; #define PG8_BAR __builtin_amdgcn_s_barrier()
; #define PG8_SCHED __builtin_amdgcn_sched_barrier(0)
; template <class Epi, class Sched, bool ALIGN_EPI = false, bool SP2 = false, bool ABLK = false, bool BBLK = false>
; __device__ __forceinline__ void gemm_phase(PG8_LAS unsigned char* lds, const Gemm g, const Sched& S, const Epi& E) {
;     ...
;             PG8_LDA(At, 1, 1); PG8_STAGE(PG8_SB(1, 0), b3, voffB); PG8_STAGE(PG8_SB(1, 1), b3 + hstepB, voffB); PG8_STAGE(PG8_SA(1, 0), a3, voffA);
;             PG8_WAIT_V(8); PG8_WAIT_L(0); PG8_BAR; PG8_MMA(1, 0, At, B0); PG8_MMA(1, 1, At, B1); PG8_BAR; PG8_SCHED;
	s_add_u32 s28, s26, 0x8000
	s_addc_u32 s29, s27, 0
	s_add_i32 s68, s68, s34
	s_mov_b32 m0, s68
	ds_read_b128 v[180:183], v150 offset:49152
	ds_read_b128 v[184:187], v150 offset:50176
	ds_read_b128 v[188:191], v150 offset:51200
	ds_read_b128 v[192:195], v150 offset:52224
	ds_read_b128 v[196:199], v150 offset:53248
	ds_read_b128 v[200:203], v150 offset:54272
	ds_read_b128 v[204:207], v150 offset:55296
	ds_read_b128 v[208:211], v150 offset:56320
	global_load_lds_dwordx4 v138, s[28:29]
	s_add_i32 m0, s68, 0x2000
	s_add_u32 s26, s26, 0xc000
	s_addc_u32 s27, s27, 0
	global_load_lds_dwordx4 v142, s[28:29]
	s_add_i32 s28, s69, s34
	s_mov_b32 m0, s28
	s_nop 0
	global_load_lds_dwordx4 v138, s[26:27]
	s_add_i32 m0, s28, 0x2000
	s_nop 0
	global_load_lds_dwordx4 v142, s[26:27]
	s_mov_b32 m0, s64
	s_nop 0
	global_load_lds_dwordx4 v136, s[24:25]
	s_mov_b32 m0, s65
	s_nop 0
	global_load_lds_dwordx4 v140, s[24:25]
	s_waitcnt vmcnt(8)
	s_waitcnt lgkmcnt(6)
	v_mfma_f32_16x16x32_bf16 v[68:71], v[52:55], v[180:183], v[68:71]
	v_mfma_f32_16x16x32_bf16 v[68:71], v[152:155], v[184:187], v[68:71]
	v_mfma_f32_16x16x32_bf16 v[64:67], v[160:163], v[184:187], v[64:67]
	v_mfma_f32_16x16x32_bf16 v[64:67], v[156:159], v[180:183], v[64:67]
	s_barrier
	s_setprio 1
	s_waitcnt lgkmcnt(0)
	v_mfma_f32_16x16x32_bf16 v[56:59], v[156:159], v[188:191], v[56:59]
	v_mfma_f32_16x16x32_bf16 v[56:59], v[160:163], v[192:195], v[56:59]
	v_mfma_f32_16x16x32_bf16 v[60:63], v[152:155], v[192:195], v[60:63]
	v_mfma_f32_16x16x32_bf16 v[60:63], v[52:55], v[188:191], v[60:63]
	v_mfma_f32_16x16x32_bf16 v[44:47], v[52:55], v[196:199], v[44:47]
	v_mfma_f32_16x16x32_bf16 v[44:47], v[152:155], v[200:203], v[44:47]
	v_mfma_f32_16x16x32_bf16 v[40:43], v[160:163], v[200:203], v[40:43]
	v_mfma_f32_16x16x32_bf16 v[40:43], v[156:159], v[196:199], v[40:43]
	v_mfma_f32_16x16x32_bf16 v[20:23], v[156:159], v[204:207], v[20:23]
	v_mfma_f32_16x16x32_bf16 v[20:23], v[160:163], v[208:211], v[20:23]
	v_mfma_f32_16x16x32_bf16 v[24:27], v[152:155], v[208:211], v[24:27]
	v_mfma_f32_16x16x32_bf16 v[24:27], v[52:55], v[204:207], v[24:27]
	s_setprio 0
	s_setprio 1
	v_mfma_f32_16x16x32_bf16 v[36:39], v[164:167], v[180:183], v[36:39]
	v_mfma_f32_16x16x32_bf16 v[52:55], v[168:171], v[184:187], v[36:39]
	v_mfma_f32_16x16x32_bf16 v[36:39], v[172:175], v[180:183], v[48:51]
	v_mfma_f32_16x16x32_bf16 v[32:35], v[164:167], v[188:191], v[32:35]
	v_mfma_f32_16x16x32_bf16 v[28:31], v[172:175], v[188:191], v[28:31]
	v_mfma_f32_16x16x32_bf16 v[16:19], v[164:167], v[196:199], v[16:19]
	v_mfma_f32_16x16x32_bf16 v[12:15], v[172:175], v[196:199], v[12:15]
	v_mfma_f32_16x16x32_bf16 v[8:11], v[164:167], v[204:207], v[8:11]
	v_mfma_f32_16x16x32_bf16 v[4:7], v[172:175], v[204:207], v[4:7]
	v_mfma_f32_16x16x32_bf16 v[48:51], v[176:179], v[184:187], v[36:39]
	v_mfma_f32_16x16x32_bf16 v[32:35], v[168:171], v[192:195], v[32:35]
	v_mfma_f32_16x16x32_bf16 v[28:31], v[176:179], v[192:195], v[28:31]
	v_mfma_f32_16x16x32_bf16 v[16:19], v[168:171], v[200:203], v[16:19]
	v_mfma_f32_16x16x32_bf16 v[12:15], v[176:179], v[200:203], v[12:15]
	v_mfma_f32_16x16x32_bf16 v[8:11], v[168:171], v[208:211], v[8:11]
	v_mfma_f32_16x16x32_bf16 v[4:7], v[176:179], v[208:211], v[4:7]
	s_setprio 0
	s_barrier
	s_add_i32 s13, s13, 2
	s_add_u32 s22, s22, 0x10000
	s_addc_u32 s23, s23, 0
	s_add_u32 s82, s82, 0x10000
	s_addc_u32 vcc_lo, vcc_lo, 0
	s_cmp_gt_u32 s13, 29
	s_cbranch_scc0 .LBB0_2111
	s_and_b64 vcc, exec, s[6:7]
	s_movk_i32 s77, 0x1000
	s_cbranch_vccz .LBB0_2114
	s_barrier
